# GEMM units: accumulator zeroing (128 v_mov per wave per unit) removed; first half-iteration of each K-loop peeled with literal-zero C operand on each accumulator's first MFMA; on top of R8
# baseline (speedup 1.0000x reference)
.LBB0_903:
	s_ashr_i32 s45, s44, 31
	s_lshl_b64 s[48:49], s[44:45], 20
	s_add_u32 s0, s10, s48
	s_addc_u32 s1, s11, s49
	s_ashr_i32 s41, s40, 31
	s_lshl_b64 s[50:51], s[40:41], 1
	s_add_u32 s48, s0, s50
	s_addc_u32 s49, s1, s51
	s_and_b64 s[58:59], s[46:47], exec
	s_cselect_b32 s41, s49, s9
	s_cselect_b32 s45, s48, s8
	s_ashr_i32 s43, s42, 31
	s_lshl_b64 s[58:59], s[42:43], 20
	s_add_u32 s0, s2, s58
	s_addc_u32 s1, s3, s59
	s_add_u32 s50, s0, s50
	s_addc_u32 s51, s1, s51
	s_and_b64 s[58:59], s[46:47], exec
	s_cselect_b32 s43, s51, s53
	s_cselect_b32 s65, s50, s52
	s_add_i32 s66, s62, -2
	s_add_u32 s67, s52, 0x100
	s_addc_u32 s68, s53, 0
	s_add_u32 s52, s8, 0x80080
	s_addc_u32 s53, s9, 0
	s_mov_b32 s8, 0
	s_nop 0
	s_cmp_eq_u32 s100, 1
	s_cbranch_scc0 .Ldefbar_skip_0
	s_mov_b32 s100, 0
	s_barrier
.Ldefbar_skip_0:
	s_add_i32 s69, s8, 2
	s_add_u32 s0, s52, 0xfff80080
	s_addc_u32 s1, s53, -1
	s_add_i32 s70, 0, 0x10000
	s_cmp_eq_u32 s66, s8
	s_cselect_b32 s59, s41, s1
	s_cselect_b32 s58, s45, s0
	s_cselect_b32 s9, s43, s68
	s_cselect_b32 s8, s65, s67
	s_add_i32 s0, 0, 0x14000
	v_add_u32_e32 v156, s70, v141
	v_add_u32_e32 v172, s0, v141
	ds_read_b128 v[144:147], v156
	ds_read_b128 v[148:151], v156 offset:1024
	ds_read_b128 v[152:155], v156 offset:2048
	ds_read_b128 v[156:159], v156 offset:3072
	ds_read_b128 v[160:163], v172
	ds_read_b128 v[164:167], v172 offset:1024
	ds_read_b128 v[168:171], v172 offset:2048
	ds_read_b128 v[172:175], v172 offset:3072
	s_add_i32 m0, s27, 0xc000
	ds_read_b128 v[176:179], v143
	ds_read_b128 v[180:183], v143 offset:1024
	ds_read_b128 v[184:187], v143 offset:2048
	ds_read_b128 v[188:191], v143 offset:3072
	ds_read_b128 v[192:195], v143 offset:4096
	ds_read_b128 v[202:205], v143 offset:5120
	ds_read_b128 v[206:209], v143 offset:6144
	ds_read_b128 v[210:213], v143 offset:7168
	global_load_lds_dwordx4 v138, s[52:53]
	s_add_i32 m0, s27, 0xe000
	s_nop 0
	global_load_lds_dwordx4 v136, s[52:53]
	s_waitcnt vmcnt(8)
	s_waitcnt lgkmcnt(0)
	s_setprio 1
	s_barrier
	v_mfma_f32_16x16x32_bf16 v[126:129], v[144:147], v[176:179], 0
	v_mfma_f32_16x16x32_bf16 v[118:121], v[152:155], v[176:179], 0
	v_mfma_f32_16x16x32_bf16 v[110:113], v[144:147], v[184:187], 0
	v_mfma_f32_16x16x32_bf16 v[102:105], v[152:155], v[184:187], 0
	v_mfma_f32_16x16x32_bf16 v[94:97], v[144:147], v[192:195], 0
	v_mfma_f32_16x16x32_bf16 v[86:89], v[152:155], v[192:195], 0
	v_mfma_f32_16x16x32_bf16 v[78:81], v[144:147], v[206:209], 0
	v_mfma_f32_16x16x32_bf16 v[70:73], v[152:155], v[206:209], 0
	v_mfma_f32_16x16x32_bf16 v[126:129], v[148:151], v[180:183], v[126:129]
	v_mfma_f32_16x16x32_bf16 v[118:121], v[156:159], v[180:183], v[118:121]
	v_mfma_f32_16x16x32_bf16 v[110:113], v[148:151], v[188:191], v[110:113]
	v_mfma_f32_16x16x32_bf16 v[102:105], v[156:159], v[188:191], v[102:105]
	v_mfma_f32_16x16x32_bf16 v[94:97], v[148:151], v[202:205], v[94:97]
	v_mfma_f32_16x16x32_bf16 v[86:89], v[156:159], v[202:205], v[86:89]
	v_mfma_f32_16x16x32_bf16 v[78:81], v[148:151], v[210:213], v[78:81]
	v_mfma_f32_16x16x32_bf16 v[70:73], v[156:159], v[210:213], v[70:73]
	v_mfma_f32_16x16x32_bf16 v[122:125], v[160:163], v[176:179], 0
	v_mfma_f32_16x16x32_bf16 v[114:117], v[168:171], v[176:179], 0
	v_mfma_f32_16x16x32_bf16 v[106:109], v[160:163], v[184:187], 0
	v_mfma_f32_16x16x32_bf16 v[98:101], v[168:171], v[184:187], 0
	v_mfma_f32_16x16x32_bf16 v[90:93], v[160:163], v[192:195], 0
	v_mfma_f32_16x16x32_bf16 v[82:85], v[168:171], v[192:195], 0
	v_mfma_f32_16x16x32_bf16 v[74:77], v[160:163], v[206:209], 0
	v_mfma_f32_16x16x32_bf16 v[66:69], v[168:171], v[206:209], 0
	v_mfma_f32_16x16x32_bf16 v[122:125], v[164:167], v[180:183], v[122:125]
	v_mfma_f32_16x16x32_bf16 v[114:117], v[172:175], v[180:183], v[114:117]
	v_mfma_f32_16x16x32_bf16 v[106:109], v[164:167], v[188:191], v[106:109]
	v_mfma_f32_16x16x32_bf16 v[98:101], v[172:175], v[188:191], v[98:101]
	v_mfma_f32_16x16x32_bf16 v[90:93], v[164:167], v[202:205], v[90:93]
	v_mfma_f32_16x16x32_bf16 v[82:85], v[172:175], v[202:205], v[82:85]
	v_mfma_f32_16x16x32_bf16 v[74:77], v[164:167], v[210:213], v[74:77]
	v_mfma_f32_16x16x32_bf16 v[66:69], v[172:175], v[210:213], v[66:69]
	s_barrier
	s_setprio 0
	s_add_i32 s1, s70, s26
	s_add_u32 s98, s8, s16
	s_addc_u32 s99, s9, s17
	s_mov_b32 m0, s1
	ds_read_b128 v[176:179], v143 offset:16384
	ds_read_b128 v[180:183], v143 offset:17408
	ds_read_b128 v[184:187], v143 offset:18432
	ds_read_b128 v[188:191], v143 offset:19456
	ds_read_b128 v[192:195], v143 offset:20480
	ds_read_b128 v[202:205], v143 offset:21504
	ds_read_b128 v[206:209], v143 offset:22528
	ds_read_b128 v[210:213], v143 offset:23552
	global_load_lds_dwordx4 v196, s[8:9]
	s_add_i32 m0, s1, 0x2000
	s_add_u32 s70, s8, 0x80000
	s_addc_u32 s71, s9, 0
	s_add_i32 s0, s0, s26
	global_load_lds_dwordx4 v130, s[8:9]
	s_mov_b32 m0, s0
	s_nop 0
	global_load_lds_dwordx4 v196, s[70:71]
	s_add_i32 m0, s0, 0x2000
	s_nop 0
	global_load_lds_dwordx4 v130, s[70:71]
	s_add_u32 s78, s58, s16
	s_addc_u32 s79, s59, s17
	s_mov_b32 m0, s27
	s_nop 0
	global_load_lds_dwordx4 v134, s[58:59]
	s_mov_b32 m0, s28
	s_nop 0
	global_load_lds_dwordx4 v132, s[58:59]
	s_waitcnt vmcnt(8)
	s_waitcnt lgkmcnt(0)
	s_setprio 1
	s_barrier
	v_mfma_f32_16x16x32_bf16 v[62:65], v[144:147], v[176:179], 0
	v_mfma_f32_16x16x32_bf16 v[54:57], v[152:155], v[176:179], 0
	v_mfma_f32_16x16x32_bf16 v[46:49], v[144:147], v[184:187], 0
	v_mfma_f32_16x16x32_bf16 v[38:41], v[152:155], v[184:187], 0
	v_mfma_f32_16x16x32_bf16 v[30:33], v[144:147], v[192:195], 0
	v_mfma_f32_16x16x32_bf16 v[22:25], v[152:155], v[192:195], 0
	v_mfma_f32_16x16x32_bf16 v[14:17], v[144:147], v[206:209], 0
	v_mfma_f32_16x16x32_bf16 v[6:9], v[152:155], v[206:209], 0
	v_mfma_f32_16x16x32_bf16 v[62:65], v[148:151], v[180:183], v[62:65]
	v_mfma_f32_16x16x32_bf16 v[54:57], v[156:159], v[180:183], v[54:57]
	v_mfma_f32_16x16x32_bf16 v[46:49], v[148:151], v[188:191], v[46:49]
	v_mfma_f32_16x16x32_bf16 v[38:41], v[156:159], v[188:191], v[38:41]
	v_mfma_f32_16x16x32_bf16 v[30:33], v[148:151], v[202:205], v[30:33]
	v_mfma_f32_16x16x32_bf16 v[22:25], v[156:159], v[202:205], v[22:25]
	v_mfma_f32_16x16x32_bf16 v[14:17], v[148:151], v[210:213], v[14:17]
	v_mfma_f32_16x16x32_bf16 v[6:9], v[156:159], v[210:213], v[6:9]
	v_mfma_f32_16x16x32_bf16 v[58:61], v[160:163], v[176:179], 0
	v_mfma_f32_16x16x32_bf16 v[50:53], v[168:171], v[176:179], 0
	v_mfma_f32_16x16x32_bf16 v[42:45], v[160:163], v[184:187], 0
	v_mfma_f32_16x16x32_bf16 v[34:37], v[168:171], v[184:187], 0
	v_mfma_f32_16x16x32_bf16 v[26:29], v[160:163], v[192:195], 0
	v_mfma_f32_16x16x32_bf16 v[18:21], v[168:171], v[192:195], 0
	v_mfma_f32_16x16x32_bf16 v[10:13], v[160:163], v[206:209], 0
	v_mfma_f32_16x16x32_bf16 v[2:5], v[168:171], v[206:209], 0
	v_mfma_f32_16x16x32_bf16 v[58:61], v[164:167], v[180:183], v[58:61]
	v_mfma_f32_16x16x32_bf16 v[50:53], v[172:175], v[180:183], v[50:53]
	v_mfma_f32_16x16x32_bf16 v[42:45], v[164:167], v[188:191], v[42:45]
	v_mfma_f32_16x16x32_bf16 v[34:37], v[172:175], v[188:191], v[34:37]
	v_mfma_f32_16x16x32_bf16 v[26:29], v[164:167], v[202:205], v[26:29]
	v_mfma_f32_16x16x32_bf16 v[18:21], v[172:175], v[202:205], v[18:21]
	v_mfma_f32_16x16x32_bf16 v[10:13], v[164:167], v[210:213], v[10:13]
	v_mfma_f32_16x16x32_bf16 v[2:5], v[172:175], v[210:213], v[2:5]
	s_barrier
	s_setprio 0
	s_branch .Lkmid_0

.Lkmid_0:
	s_add_i32 s0, 0, 0x18000
	s_add_i32 s1, 0, 0x1c000
	v_add_u32_e32 v156, s0, v141
	v_add_u32_e32 v172, s1, v141
	ds_read_b128 v[144:147], v156
	ds_read_b128 v[148:151], v156 offset:1024
	ds_read_b128 v[152:155], v156 offset:2048
	ds_read_b128 v[156:159], v156 offset:3072
	ds_read_b128 v[160:163], v172
	ds_read_b128 v[164:167], v172 offset:1024
	ds_read_b128 v[168:171], v172 offset:2048
	ds_read_b128 v[172:175], v172 offset:3072
	s_add_u32 s58, s58, 0x80000
	s_addc_u32 s59, s59, 0
	s_mov_b32 m0, s29
	ds_read_b128 v[176:179], v143 offset:32768
	ds_read_b128 v[180:183], v143 offset:33792
	ds_read_b128 v[184:187], v143 offset:34816
	ds_read_b128 v[188:191], v143 offset:35840
	ds_read_b128 v[192:195], v143 offset:36864
	ds_read_b128 v[202:205], v143 offset:37888
	ds_read_b128 v[206:209], v143 offset:38912
	ds_read_b128 v[210:213], v143 offset:39936
	global_load_lds_dwordx4 v134, s[58:59]
	s_mov_b32 m0, s30
	s_nop 0
	global_load_lds_dwordx4 v132, s[58:59]
	s_waitcnt vmcnt(8)
	s_waitcnt lgkmcnt(0)
	s_setprio 1
	s_barrier
	v_mfma_f32_16x16x32_bf16 v[126:129], v[144:147], v[176:179], v[126:129]
	v_mfma_f32_16x16x32_bf16 v[118:121], v[152:155], v[176:179], v[118:121]
	v_mfma_f32_16x16x32_bf16 v[110:113], v[144:147], v[184:187], v[110:113]
	v_mfma_f32_16x16x32_bf16 v[102:105], v[152:155], v[184:187], v[102:105]
	v_mfma_f32_16x16x32_bf16 v[94:97], v[144:147], v[192:195], v[94:97]
	v_mfma_f32_16x16x32_bf16 v[86:89], v[152:155], v[192:195], v[86:89]
	v_mfma_f32_16x16x32_bf16 v[78:81], v[144:147], v[206:209], v[78:81]
	v_mfma_f32_16x16x32_bf16 v[70:73], v[152:155], v[206:209], v[70:73]
	v_mfma_f32_16x16x32_bf16 v[126:129], v[148:151], v[180:183], v[126:129]
	v_mfma_f32_16x16x32_bf16 v[118:121], v[156:159], v[180:183], v[118:121]
	v_mfma_f32_16x16x32_bf16 v[110:113], v[148:151], v[188:191], v[110:113]
	v_mfma_f32_16x16x32_bf16 v[102:105], v[156:159], v[188:191], v[102:105]
	v_mfma_f32_16x16x32_bf16 v[94:97], v[148:151], v[202:205], v[94:97]
	v_mfma_f32_16x16x32_bf16 v[86:89], v[156:159], v[202:205], v[86:89]
	v_mfma_f32_16x16x32_bf16 v[78:81], v[148:151], v[210:213], v[78:81]
	v_mfma_f32_16x16x32_bf16 v[70:73], v[156:159], v[210:213], v[70:73]
	v_mfma_f32_16x16x32_bf16 v[122:125], v[160:163], v[176:179], v[122:125]
	v_mfma_f32_16x16x32_bf16 v[114:117], v[168:171], v[176:179], v[114:117]
	v_mfma_f32_16x16x32_bf16 v[106:109], v[160:163], v[184:187], v[106:109]
	v_mfma_f32_16x16x32_bf16 v[98:101], v[168:171], v[184:187], v[98:101]
	v_mfma_f32_16x16x32_bf16 v[90:93], v[160:163], v[192:195], v[90:93]
	v_mfma_f32_16x16x32_bf16 v[82:85], v[168:171], v[192:195], v[82:85]
	v_mfma_f32_16x16x32_bf16 v[74:77], v[160:163], v[206:209], v[74:77]
	v_mfma_f32_16x16x32_bf16 v[66:69], v[168:171], v[206:209], v[66:69]
	v_mfma_f32_16x16x32_bf16 v[122:125], v[164:167], v[180:183], v[122:125]
	v_mfma_f32_16x16x32_bf16 v[114:117], v[172:175], v[180:183], v[114:117]
	v_mfma_f32_16x16x32_bf16 v[106:109], v[164:167], v[188:191], v[106:109]
	v_mfma_f32_16x16x32_bf16 v[98:101], v[172:175], v[188:191], v[98:101]
	v_mfma_f32_16x16x32_bf16 v[90:93], v[164:167], v[202:205], v[90:93]
	v_mfma_f32_16x16x32_bf16 v[82:85], v[172:175], v[202:205], v[82:85]
	v_mfma_f32_16x16x32_bf16 v[74:77], v[164:167], v[210:213], v[74:77]
	v_mfma_f32_16x16x32_bf16 v[66:69], v[172:175], v[210:213], v[66:69]
	s_barrier
	s_setprio 0
	s_add_i32 s0, s0, s26
	s_mov_b32 m0, s0
	ds_read_b128 v[176:179], v143 offset:49152
	ds_read_b128 v[180:183], v143 offset:50176
	ds_read_b128 v[184:187], v143 offset:51200
	ds_read_b128 v[188:191], v143 offset:52224
	ds_read_b128 v[192:195], v143 offset:53248
	ds_read_b128 v[202:205], v143 offset:54272
	ds_read_b128 v[206:209], v143 offset:55296
	ds_read_b128 v[210:213], v143 offset:56320
	global_load_lds_dwordx4 v196, s[98:99]
	s_add_i32 m0, s0, 0x2000
	s_add_u32 s8, s8, 0x80080
	s_addc_u32 s9, s9, 0
	s_add_i32 s0, s1, s26
	global_load_lds_dwordx4 v130, s[98:99]
	s_mov_b32 m0, s0
	s_nop 0
	global_load_lds_dwordx4 v196, s[8:9]
	s_add_i32 m0, s0, 0x2000
	s_nop 0
	global_load_lds_dwordx4 v130, s[8:9]
	s_mov_b32 m0, s31
	s_nop 0
	global_load_lds_dwordx4 v134, s[78:79]
	s_mov_b32 m0, s34
	s_nop 0
	global_load_lds_dwordx4 v132, s[78:79]
	s_waitcnt vmcnt(8)
	s_waitcnt lgkmcnt(0)
	s_setprio 1
	s_barrier
	v_mfma_f32_16x16x32_bf16 v[62:65], v[144:147], v[176:179], v[62:65]
	v_mfma_f32_16x16x32_bf16 v[54:57], v[152:155], v[176:179], v[54:57]
	v_mfma_f32_16x16x32_bf16 v[46:49], v[144:147], v[184:187], v[46:49]
	v_mfma_f32_16x16x32_bf16 v[38:41], v[152:155], v[184:187], v[38:41]
	v_mfma_f32_16x16x32_bf16 v[30:33], v[144:147], v[192:195], v[30:33]
	v_mfma_f32_16x16x32_bf16 v[22:25], v[152:155], v[192:195], v[22:25]
	v_mfma_f32_16x16x32_bf16 v[14:17], v[144:147], v[206:209], v[14:17]
	v_mfma_f32_16x16x32_bf16 v[6:9], v[152:155], v[206:209], v[6:9]
	v_mfma_f32_16x16x32_bf16 v[62:65], v[148:151], v[180:183], v[62:65]
	v_mfma_f32_16x16x32_bf16 v[54:57], v[156:159], v[180:183], v[54:57]
	v_mfma_f32_16x16x32_bf16 v[46:49], v[148:151], v[188:191], v[46:49]
	v_mfma_f32_16x16x32_bf16 v[38:41], v[156:159], v[188:191], v[38:41]
	v_mfma_f32_16x16x32_bf16 v[30:33], v[148:151], v[202:205], v[30:33]
	v_mfma_f32_16x16x32_bf16 v[22:25], v[156:159], v[202:205], v[22:25]
	v_mfma_f32_16x16x32_bf16 v[14:17], v[148:151], v[210:213], v[14:17]
	v_mfma_f32_16x16x32_bf16 v[6:9], v[156:159], v[210:213], v[6:9]
	v_mfma_f32_16x16x32_bf16 v[58:61], v[160:163], v[176:179], v[58:61]
	v_mfma_f32_16x16x32_bf16 v[50:53], v[168:171], v[176:179], v[50:53]
	v_mfma_f32_16x16x32_bf16 v[42:45], v[160:163], v[184:187], v[42:45]
	v_mfma_f32_16x16x32_bf16 v[34:37], v[168:171], v[184:187], v[34:37]
	v_mfma_f32_16x16x32_bf16 v[26:29], v[160:163], v[192:195], v[26:29]
	v_mfma_f32_16x16x32_bf16 v[18:21], v[168:171], v[192:195], v[18:21]
	v_mfma_f32_16x16x32_bf16 v[10:13], v[160:163], v[206:209], v[10:13]
	v_mfma_f32_16x16x32_bf16 v[2:5], v[168:171], v[206:209], v[2:5]
	v_mfma_f32_16x16x32_bf16 v[58:61], v[164:167], v[180:183], v[58:61]
	v_mfma_f32_16x16x32_bf16 v[50:53], v[172:175], v[180:183], v[50:53]
	v_mfma_f32_16x16x32_bf16 v[42:45], v[164:167], v[188:191], v[42:45]
	v_mfma_f32_16x16x32_bf16 v[34:37], v[172:175], v[188:191], v[34:37]
	v_mfma_f32_16x16x32_bf16 v[26:29], v[164:167], v[202:205], v[26:29]
	v_mfma_f32_16x16x32_bf16 v[18:21], v[172:175], v[202:205], v[18:21]
	v_mfma_f32_16x16x32_bf16 v[10:13], v[164:167], v[210:213], v[10:13]
	v_mfma_f32_16x16x32_bf16 v[2:5], v[172:175], v[210:213], v[2:5]
	s_barrier
	s_setprio 0
	s_add_u32 s67, s67, 0x100
	s_addc_u32 s68, s68, 0
	s_add_u32 s52, s52, 0x100
	s_addc_u32 s53, s53, 0
	s_cmp_ge_i32 s69, s62
	s_mov_b32 s8, s69
	s_cbranch_scc0 .LBB0_904
	s_and_b64 vcc, exec, s[38:39]
	s_cbranch_vccz .LBB0_907
	s_barrier

.LBB0_986:
	s_add_i32 s41, s69, -2
	s_add_u32 s70, s8, 0x100
	s_addc_u32 s71, s9, 0
	s_mov_b32 s50, 0
	s_nop 0
	s_cmp_eq_u32 s100, 1
	s_cbranch_scc0 .Ldefbar_skip_1
	s_mov_b32 s100, 0
	s_barrier
.Ldefbar_skip_1:
	s_add_i32 s72, s50, 2
	s_add_u32 s8, s48, 0x100
	s_addc_u32 s9, s49, 0
	s_add_i32 s0, 0, 0x10000
	s_cmp_eq_u32 s41, s50
	s_cselect_b32 s53, s45, s9
	s_cselect_b32 s52, s44, s8
	s_cselect_b32 s51, s47, s71
	s_cselect_b32 s50, s46, s70
	s_add_i32 s1, 0, 0x14000
	v_add_u32_e32 v142, s0, v188
	v_add_u32_e32 v172, s1, v188
	ds_read_b128 v[130:133], v142
	ds_read_b128 v[134:137], v142 offset:1024
	ds_read_b128 v[138:141], v142 offset:2048
	ds_read_b128 v[142:145], v142 offset:3072
	ds_read_b128 v[146:149], v172
	ds_read_b128 v[164:167], v172 offset:1024
	ds_read_b128 v[168:171], v172 offset:2048
	ds_read_b128 v[172:175], v172 offset:3072
	v_lshl_add_u64 v[194:195], s[48:49], 0, v[162:163]
	s_add_i32 m0, s27, 0xc000
	ds_read_b128 v[176:179], v189
	ds_read_b128 v[180:183], v189 offset:1024
	ds_read_b128 v[184:187], v189 offset:2048
	ds_read_b128 v[190:193], v189 offset:3072
	ds_read_b128 v[202:205], v189 offset:4096
	ds_read_b128 v[206:209], v189 offset:5120
	ds_read_b128 v[210:213], v189 offset:6144
	ds_read_b128 v[214:217], v189 offset:7168
	global_load_lds_dwordx4 v[194:195], off
	v_lshl_add_u64 v[194:195], s[48:49], 0, v[160:161]
	s_add_i32 m0, s27, 0xe000
	s_nop 0
	global_load_lds_dwordx4 v[194:195], off
	s_waitcnt vmcnt(8)
	s_waitcnt lgkmcnt(0)
	s_setprio 1
	s_barrier
	v_mfma_f32_16x16x32_bf16 v[126:129], v[130:133], v[176:179], 0
	v_mfma_f32_16x16x32_bf16 v[122:125], v[138:141], v[176:179], 0
	v_mfma_f32_16x16x32_bf16 v[110:113], v[130:133], v[184:187], 0
	v_mfma_f32_16x16x32_bf16 v[106:109], v[138:141], v[184:187], 0
	v_mfma_f32_16x16x32_bf16 v[98:101], v[130:133], v[202:205], 0
	v_mfma_f32_16x16x32_bf16 v[90:93], v[138:141], v[202:205], 0
	v_mfma_f32_16x16x32_bf16 v[82:85], v[130:133], v[210:213], 0
	v_mfma_f32_16x16x32_bf16 v[74:77], v[138:141], v[210:213], 0
	v_mfma_f32_16x16x32_bf16 v[126:129], v[134:137], v[180:183], v[126:129]
	v_mfma_f32_16x16x32_bf16 v[122:125], v[142:145], v[180:183], v[122:125]
	v_mfma_f32_16x16x32_bf16 v[110:113], v[134:137], v[190:193], v[110:113]
	v_mfma_f32_16x16x32_bf16 v[106:109], v[142:145], v[190:193], v[106:109]
	v_mfma_f32_16x16x32_bf16 v[98:101], v[134:137], v[206:209], v[98:101]
	v_mfma_f32_16x16x32_bf16 v[90:93], v[142:145], v[206:209], v[90:93]
	v_mfma_f32_16x16x32_bf16 v[82:85], v[134:137], v[214:217], v[82:85]
	v_mfma_f32_16x16x32_bf16 v[74:77], v[142:145], v[214:217], v[74:77]
	v_mfma_f32_16x16x32_bf16 v[118:121], v[146:149], v[176:179], 0
	v_mfma_f32_16x16x32_bf16 v[114:117], v[168:171], v[176:179], 0
	v_mfma_f32_16x16x32_bf16 v[102:105], v[146:149], v[184:187], 0
	v_mfma_f32_16x16x32_bf16 v[94:97], v[168:171], v[184:187], 0
	v_mfma_f32_16x16x32_bf16 v[86:89], v[146:149], v[202:205], 0
	v_mfma_f32_16x16x32_bf16 v[78:81], v[168:171], v[202:205], 0
	v_mfma_f32_16x16x32_bf16 v[70:73], v[146:149], v[210:213], 0
	v_mfma_f32_16x16x32_bf16 v[66:69], v[168:171], v[210:213], 0
	v_mfma_f32_16x16x32_bf16 v[118:121], v[164:167], v[180:183], v[118:121]
	v_mfma_f32_16x16x32_bf16 v[114:117], v[172:175], v[180:183], v[114:117]
	v_mfma_f32_16x16x32_bf16 v[102:105], v[164:167], v[190:193], v[102:105]
	v_mfma_f32_16x16x32_bf16 v[94:97], v[172:175], v[190:193], v[94:97]
	v_mfma_f32_16x16x32_bf16 v[86:89], v[164:167], v[206:209], v[86:89]
	v_mfma_f32_16x16x32_bf16 v[78:81], v[172:175], v[206:209], v[78:81]
	v_mfma_f32_16x16x32_bf16 v[70:73], v[164:167], v[214:217], v[70:73]
	v_mfma_f32_16x16x32_bf16 v[66:69], v[172:175], v[214:217], v[66:69]
	s_barrier
	s_setprio 0
	s_add_i32 s0, s0, s26
	s_add_u32 s98, s50, s16
	s_addc_u32 s99, s51, s17
	s_mov_b32 m0, s0
	ds_read_b128 v[176:179], v189 offset:16384
	ds_read_b128 v[180:183], v189 offset:17408
	ds_read_b128 v[184:187], v189 offset:18432
	ds_read_b128 v[190:193], v189 offset:19456
	ds_read_b128 v[202:205], v189 offset:20480
	ds_read_b128 v[206:209], v189 offset:21504
	ds_read_b128 v[210:213], v189 offset:22528
	ds_read_b128 v[214:217], v189 offset:23552
	global_load_lds_dwordx4 v196, s[50:51]
	s_add_i32 m0, s0, 0x2000
	s_add_u32 s48, s50, 0x158000
	s_addc_u32 s49, s51, 0
	s_add_i32 s0, s1, s26
	global_load_lds_dwordx4 v154, s[50:51]
	s_mov_b32 m0, s0
	s_nop 0
	global_load_lds_dwordx4 v196, s[48:49]
	s_add_i32 m0, s0, 0x2000
	s_nop 0
	global_load_lds_dwordx4 v154, s[48:49]
	s_add_u32 s78, s52, s16
	s_addc_u32 s79, s53, s17
	s_mov_b32 m0, s27
	s_nop 0
	global_load_lds_dwordx4 v150, s[52:53]
	s_mov_b32 m0, s28
	s_nop 0
	global_load_lds_dwordx4 v152, s[52:53]
	s_waitcnt vmcnt(8)
	s_waitcnt lgkmcnt(0)
	s_setprio 1
	s_barrier
	v_mfma_f32_16x16x32_bf16 v[62:65], v[130:133], v[176:179], 0
	v_mfma_f32_16x16x32_bf16 v[58:61], v[138:141], v[176:179], 0
	v_mfma_f32_16x16x32_bf16 v[50:53], v[130:133], v[184:187], 0
	v_mfma_f32_16x16x32_bf16 v[42:45], v[138:141], v[184:187], 0
	v_mfma_f32_16x16x32_bf16 v[34:37], v[130:133], v[202:205], 0
	v_mfma_f32_16x16x32_bf16 v[26:29], v[138:141], v[202:205], 0
	v_mfma_f32_16x16x32_bf16 v[18:21], v[130:133], v[210:213], 0
	v_mfma_f32_16x16x32_bf16 v[10:13], v[138:141], v[210:213], 0
	v_mfma_f32_16x16x32_bf16 v[62:65], v[134:137], v[180:183], v[62:65]
	v_mfma_f32_16x16x32_bf16 v[58:61], v[142:145], v[180:183], v[58:61]
	v_mfma_f32_16x16x32_bf16 v[50:53], v[134:137], v[190:193], v[50:53]
	v_mfma_f32_16x16x32_bf16 v[42:45], v[142:145], v[190:193], v[42:45]
	v_mfma_f32_16x16x32_bf16 v[34:37], v[134:137], v[206:209], v[34:37]
	v_mfma_f32_16x16x32_bf16 v[26:29], v[142:145], v[206:209], v[26:29]
	v_mfma_f32_16x16x32_bf16 v[18:21], v[134:137], v[214:217], v[18:21]
	v_mfma_f32_16x16x32_bf16 v[10:13], v[142:145], v[214:217], v[10:13]
	v_mfma_f32_16x16x32_bf16 v[54:57], v[146:149], v[176:179], 0
	v_mfma_f32_16x16x32_bf16 v[46:49], v[168:171], v[176:179], 0
	v_mfma_f32_16x16x32_bf16 v[38:41], v[146:149], v[184:187], 0
	v_mfma_f32_16x16x32_bf16 v[30:33], v[168:171], v[184:187], 0
	v_mfma_f32_16x16x32_bf16 v[22:25], v[146:149], v[202:205], 0
	v_mfma_f32_16x16x32_bf16 v[14:17], v[168:171], v[202:205], 0
	v_mfma_f32_16x16x32_bf16 v[6:9], v[146:149], v[210:213], 0
	v_mfma_f32_16x16x32_bf16 v[2:5], v[168:171], v[210:213], 0
	v_mfma_f32_16x16x32_bf16 v[54:57], v[164:167], v[180:183], v[54:57]
	v_mfma_f32_16x16x32_bf16 v[46:49], v[172:175], v[180:183], v[46:49]
	v_mfma_f32_16x16x32_bf16 v[38:41], v[164:167], v[190:193], v[38:41]
	v_mfma_f32_16x16x32_bf16 v[30:33], v[172:175], v[190:193], v[30:33]
	v_mfma_f32_16x16x32_bf16 v[22:25], v[164:167], v[206:209], v[22:25]
	v_mfma_f32_16x16x32_bf16 v[14:17], v[172:175], v[206:209], v[14:17]
	v_mfma_f32_16x16x32_bf16 v[6:9], v[164:167], v[214:217], v[6:9]
	v_mfma_f32_16x16x32_bf16 v[2:5], v[172:175], v[214:217], v[2:5]
	s_barrier
	s_setprio 0
	s_branch .Lkmid_1

.Lkmid_1:
	s_add_i32 s0, 0, 0x18000
	s_add_i32 s1, 0, 0x1c000
	v_add_u32_e32 v142, s0, v188
	v_add_u32_e32 v172, s1, v188
	ds_read_b128 v[130:133], v142
	ds_read_b128 v[134:137], v142 offset:1024
	ds_read_b128 v[138:141], v142 offset:2048
	ds_read_b128 v[142:145], v142 offset:3072
	ds_read_b128 v[146:149], v172
	ds_read_b128 v[164:167], v172 offset:1024
	ds_read_b128 v[168:171], v172 offset:2048
	ds_read_b128 v[172:175], v172 offset:3072
	s_add_u32 s48, s52, 0x158000
	s_addc_u32 s49, s53, 0
	s_mov_b32 m0, s29
	ds_read_b128 v[176:179], v189 offset:32768
	ds_read_b128 v[180:183], v189 offset:33792
	ds_read_b128 v[184:187], v189 offset:34816
	ds_read_b128 v[190:193], v189 offset:35840
	ds_read_b128 v[202:205], v189 offset:36864
	ds_read_b128 v[206:209], v189 offset:37888
	ds_read_b128 v[210:213], v189 offset:38912
	ds_read_b128 v[214:217], v189 offset:39936
	global_load_lds_dwordx4 v150, s[48:49]
	s_mov_b32 m0, s30
	s_nop 0
	global_load_lds_dwordx4 v152, s[48:49]
	s_waitcnt vmcnt(8)
	s_waitcnt lgkmcnt(0)
	s_setprio 1
	s_barrier
	v_mfma_f32_16x16x32_bf16 v[126:129], v[130:133], v[176:179], v[126:129]
	v_mfma_f32_16x16x32_bf16 v[122:125], v[138:141], v[176:179], v[122:125]
	v_mfma_f32_16x16x32_bf16 v[110:113], v[130:133], v[184:187], v[110:113]
	v_mfma_f32_16x16x32_bf16 v[106:109], v[138:141], v[184:187], v[106:109]
	v_mfma_f32_16x16x32_bf16 v[98:101], v[130:133], v[202:205], v[98:101]
	v_mfma_f32_16x16x32_bf16 v[90:93], v[138:141], v[202:205], v[90:93]
	v_mfma_f32_16x16x32_bf16 v[82:85], v[130:133], v[210:213], v[82:85]
	v_mfma_f32_16x16x32_bf16 v[74:77], v[138:141], v[210:213], v[74:77]
	v_mfma_f32_16x16x32_bf16 v[126:129], v[134:137], v[180:183], v[126:129]
	v_mfma_f32_16x16x32_bf16 v[122:125], v[142:145], v[180:183], v[122:125]
	v_mfma_f32_16x16x32_bf16 v[110:113], v[134:137], v[190:193], v[110:113]
	v_mfma_f32_16x16x32_bf16 v[106:109], v[142:145], v[190:193], v[106:109]
	v_mfma_f32_16x16x32_bf16 v[98:101], v[134:137], v[206:209], v[98:101]
	v_mfma_f32_16x16x32_bf16 v[90:93], v[142:145], v[206:209], v[90:93]
	v_mfma_f32_16x16x32_bf16 v[82:85], v[134:137], v[214:217], v[82:85]
	v_mfma_f32_16x16x32_bf16 v[74:77], v[142:145], v[214:217], v[74:77]
	v_mfma_f32_16x16x32_bf16 v[118:121], v[146:149], v[176:179], v[118:121]
	v_mfma_f32_16x16x32_bf16 v[114:117], v[168:171], v[176:179], v[114:117]
	v_mfma_f32_16x16x32_bf16 v[102:105], v[146:149], v[184:187], v[102:105]
	v_mfma_f32_16x16x32_bf16 v[94:97], v[168:171], v[184:187], v[94:97]
	v_mfma_f32_16x16x32_bf16 v[86:89], v[146:149], v[202:205], v[86:89]
	v_mfma_f32_16x16x32_bf16 v[78:81], v[168:171], v[202:205], v[78:81]
	v_mfma_f32_16x16x32_bf16 v[70:73], v[146:149], v[210:213], v[70:73]
	v_mfma_f32_16x16x32_bf16 v[66:69], v[168:171], v[210:213], v[66:69]
	v_mfma_f32_16x16x32_bf16 v[118:121], v[164:167], v[180:183], v[118:121]
	v_mfma_f32_16x16x32_bf16 v[114:117], v[172:175], v[180:183], v[114:117]
	v_mfma_f32_16x16x32_bf16 v[102:105], v[164:167], v[190:193], v[102:105]
	v_mfma_f32_16x16x32_bf16 v[94:97], v[172:175], v[190:193], v[94:97]
	v_mfma_f32_16x16x32_bf16 v[86:89], v[164:167], v[206:209], v[86:89]
	v_mfma_f32_16x16x32_bf16 v[78:81], v[172:175], v[206:209], v[78:81]
	v_mfma_f32_16x16x32_bf16 v[70:73], v[164:167], v[214:217], v[70:73]
	v_mfma_f32_16x16x32_bf16 v[66:69], v[172:175], v[214:217], v[66:69]
	s_barrier
	s_setprio 0
	s_add_i32 s0, s0, s26
	s_mov_b32 m0, s0
	ds_read_b128 v[176:179], v189 offset:49152
	ds_read_b128 v[180:183], v189 offset:50176
	ds_read_b128 v[184:187], v189 offset:51200
	ds_read_b128 v[190:193], v189 offset:52224
	ds_read_b128 v[202:205], v189 offset:53248
	ds_read_b128 v[206:209], v189 offset:54272
	ds_read_b128 v[210:213], v189 offset:55296
	ds_read_b128 v[214:217], v189 offset:56320
	global_load_lds_dwordx4 v196, s[98:99]
	s_add_i32 m0, s0, 0x2000
	s_add_u32 s48, s50, 0x158080
	s_addc_u32 s49, s51, 0
	s_add_i32 s0, s1, s26
	global_load_lds_dwordx4 v154, s[98:99]
	s_mov_b32 m0, s0
	s_nop 0
	global_load_lds_dwordx4 v196, s[48:49]
	s_add_i32 m0, s0, 0x2000
	s_nop 0
	global_load_lds_dwordx4 v154, s[48:49]
	s_mov_b32 m0, s35
	s_nop 0
	global_load_lds_dwordx4 v150, s[78:79]
	s_mov_b32 m0, s58
	s_nop 0
	global_load_lds_dwordx4 v152, s[78:79]
	s_waitcnt vmcnt(8)
	s_waitcnt lgkmcnt(0)
	s_setprio 1
	s_barrier
	v_mfma_f32_16x16x32_bf16 v[62:65], v[130:133], v[176:179], v[62:65]
	v_mfma_f32_16x16x32_bf16 v[58:61], v[138:141], v[176:179], v[58:61]
	v_mfma_f32_16x16x32_bf16 v[50:53], v[130:133], v[184:187], v[50:53]
	v_mfma_f32_16x16x32_bf16 v[42:45], v[138:141], v[184:187], v[42:45]
	v_mfma_f32_16x16x32_bf16 v[34:37], v[130:133], v[202:205], v[34:37]
	v_mfma_f32_16x16x32_bf16 v[26:29], v[138:141], v[202:205], v[26:29]
	v_mfma_f32_16x16x32_bf16 v[18:21], v[130:133], v[210:213], v[18:21]
	v_mfma_f32_16x16x32_bf16 v[10:13], v[138:141], v[210:213], v[10:13]
	v_mfma_f32_16x16x32_bf16 v[62:65], v[134:137], v[180:183], v[62:65]
	v_mfma_f32_16x16x32_bf16 v[58:61], v[142:145], v[180:183], v[58:61]
	v_mfma_f32_16x16x32_bf16 v[50:53], v[134:137], v[190:193], v[50:53]
	v_mfma_f32_16x16x32_bf16 v[42:45], v[142:145], v[190:193], v[42:45]
	v_mfma_f32_16x16x32_bf16 v[34:37], v[134:137], v[206:209], v[34:37]
	v_mfma_f32_16x16x32_bf16 v[26:29], v[142:145], v[206:209], v[26:29]
	v_mfma_f32_16x16x32_bf16 v[18:21], v[134:137], v[214:217], v[18:21]
	v_mfma_f32_16x16x32_bf16 v[10:13], v[142:145], v[214:217], v[10:13]
	v_mfma_f32_16x16x32_bf16 v[54:57], v[146:149], v[176:179], v[54:57]
	v_mfma_f32_16x16x32_bf16 v[46:49], v[168:171], v[176:179], v[46:49]
	v_mfma_f32_16x16x32_bf16 v[38:41], v[146:149], v[184:187], v[38:41]
	v_mfma_f32_16x16x32_bf16 v[30:33], v[168:171], v[184:187], v[30:33]
	v_mfma_f32_16x16x32_bf16 v[22:25], v[146:149], v[202:205], v[22:25]
	v_mfma_f32_16x16x32_bf16 v[14:17], v[168:171], v[202:205], v[14:17]
	v_mfma_f32_16x16x32_bf16 v[6:9], v[146:149], v[210:213], v[6:9]
	v_mfma_f32_16x16x32_bf16 v[2:5], v[168:171], v[210:213], v[2:5]
	v_mfma_f32_16x16x32_bf16 v[54:57], v[164:167], v[180:183], v[54:57]
	v_mfma_f32_16x16x32_bf16 v[46:49], v[172:175], v[180:183], v[46:49]
	v_mfma_f32_16x16x32_bf16 v[38:41], v[164:167], v[190:193], v[38:41]
	v_mfma_f32_16x16x32_bf16 v[30:33], v[172:175], v[190:193], v[30:33]
	v_mfma_f32_16x16x32_bf16 v[22:25], v[164:167], v[206:209], v[22:25]
	v_mfma_f32_16x16x32_bf16 v[14:17], v[172:175], v[206:209], v[14:17]
	v_mfma_f32_16x16x32_bf16 v[6:9], v[164:167], v[214:217], v[6:9]
	v_mfma_f32_16x16x32_bf16 v[2:5], v[172:175], v[214:217], v[2:5]
	s_barrier
	s_setprio 0
	s_add_u32 s70, s70, 0x100
	s_addc_u32 s71, s71, 0
	s_cmp_ge_i32 s72, s69
	s_mov_b64 s[48:49], s[8:9]
	s_mov_b32 s50, s72
	s_cbranch_scc0 .LBB0_987
	s_and_b64 vcc, exec, s[38:39]
	s_cbranch_vccz .LBB0_990
	s_barrier

.LBB0_1134:
	s_ashr_i32 s47, s46, 31
	s_lshl_b64 s[50:51], s[46:47], 20
	s_add_u32 s0, s2, s50
	s_addc_u32 s1, s3, s51
	s_ashr_i32 s43, s42, 31
	s_lshl_b64 s[52:53], s[42:43], 1
	s_add_u32 s50, s0, s52
	s_addc_u32 s51, s1, s53
	s_and_b64 s[62:63], s[48:49], exec
	s_cselect_b32 s43, s51, s9
	s_cselect_b32 s47, s50, s8
	s_ashr_i32 s45, s44, 31
	s_lshl_b64 s[62:63], s[44:45], 20
	s_add_u32 s0, s10, s62
	s_addc_u32 s1, s11, s63
	s_add_u32 s52, s0, s52
	s_addc_u32 s53, s1, s53
	s_and_b64 s[62:63], s[48:49], exec
	s_cselect_b32 s45, s53, s59
	s_cselect_b32 s67, s52, s58
	s_add_i32 s68, s64, -2
	s_add_u32 s69, s58, 0x100
	s_addc_u32 s70, s59, 0
	s_add_u32 s58, s8, 0x80080
	s_addc_u32 s59, s9, 0
	s_mov_b32 s8, 0
	s_nop 0
	s_cmp_eq_u32 s100, 1
	s_cbranch_scc0 .Ldefbar_skip_2
	s_mov_b32 s100, 0
	s_barrier
.Ldefbar_skip_2:
	s_add_i32 s71, s8, 2
	s_add_u32 s0, s58, 0xfff80080
	s_addc_u32 s1, s59, -1
	s_add_i32 s72, 0, 0x10000
	s_cmp_eq_u32 s68, s8
	s_cselect_b32 s63, s43, s1
	s_cselect_b32 s62, s47, s0
	v_add_u32_e32 v146, s72, v149
	s_cselect_b32 s9, s45, s70
	s_cselect_b32 s8, s67, s69
	s_add_i32 s0, 0, 0x14000
	ds_read_b128 v[142:145], v146
	ds_read_b128 v[152:155], v146 offset:1024
	ds_read_b128 v[156:159], v146 offset:2048
	ds_read_b128 v[160:163], v146 offset:3072
	v_add_u32_e32 v146, s0, v149
	ds_read_b128 v[164:167], v146
	ds_read_b128 v[168:171], v146 offset:1024
	ds_read_b128 v[172:175], v146 offset:2048
	ds_read_b128 v[176:179], v146 offset:3072
	s_add_i32 m0, s27, 0xc000
	ds_read_b128 v[180:183], v151
	ds_read_b128 v[184:187], v151 offset:1024
	ds_read_b128 v[188:191], v151 offset:2048
	ds_read_b128 v[192:195], v151 offset:3072
	ds_read_b128 v[202:205], v151 offset:4096
	ds_read_b128 v[206:209], v151 offset:5120
	ds_read_b128 v[210:213], v151 offset:6144
	ds_read_b128 v[214:217], v151 offset:7168
	global_load_lds_dwordx4 v140, s[58:59]
	s_add_i32 m0, s27, 0xe000
	s_nop 0
	global_load_lds_dwordx4 v138, s[58:59]
	s_waitcnt vmcnt(8)
	s_waitcnt lgkmcnt(0)
	s_setprio 1
	s_barrier
	v_mfma_f32_16x16x32_bf16 v[126:129], v[142:145], v[180:183], 0
	v_mfma_f32_16x16x32_bf16 v[122:125], v[156:159], v[180:183], 0
	v_mfma_f32_16x16x32_bf16 v[118:121], v[142:145], v[188:191], 0
	v_mfma_f32_16x16x32_bf16 v[110:113], v[156:159], v[188:191], 0
	v_mfma_f32_16x16x32_bf16 v[102:105], v[142:145], v[202:205], 0
	v_mfma_f32_16x16x32_bf16 v[94:97], v[156:159], v[202:205], 0
	v_mfma_f32_16x16x32_bf16 v[86:89], v[142:145], v[210:213], 0
	v_mfma_f32_16x16x32_bf16 v[78:81], v[156:159], v[210:213], 0
	v_mfma_f32_16x16x32_bf16 v[126:129], v[152:155], v[184:187], v[126:129]
	v_mfma_f32_16x16x32_bf16 v[122:125], v[160:163], v[184:187], v[122:125]
	v_mfma_f32_16x16x32_bf16 v[118:121], v[152:155], v[192:195], v[118:121]
	v_mfma_f32_16x16x32_bf16 v[110:113], v[160:163], v[192:195], v[110:113]
	v_mfma_f32_16x16x32_bf16 v[102:105], v[152:155], v[206:209], v[102:105]
	v_mfma_f32_16x16x32_bf16 v[94:97], v[160:163], v[206:209], v[94:97]
	v_mfma_f32_16x16x32_bf16 v[86:89], v[152:155], v[214:217], v[86:89]
	v_mfma_f32_16x16x32_bf16 v[78:81], v[160:163], v[214:217], v[78:81]
	v_mfma_f32_16x16x32_bf16 v[114:117], v[164:167], v[180:183], 0
	v_mfma_f32_16x16x32_bf16 v[106:109], v[172:175], v[180:183], 0
	v_mfma_f32_16x16x32_bf16 v[98:101], v[164:167], v[188:191], 0
	v_mfma_f32_16x16x32_bf16 v[90:93], v[172:175], v[188:191], 0
	v_mfma_f32_16x16x32_bf16 v[82:85], v[164:167], v[202:205], 0
	v_mfma_f32_16x16x32_bf16 v[74:77], v[172:175], v[202:205], 0
	v_mfma_f32_16x16x32_bf16 v[70:73], v[164:167], v[210:213], 0
	v_mfma_f32_16x16x32_bf16 v[66:69], v[172:175], v[210:213], 0
	v_mfma_f32_16x16x32_bf16 v[114:117], v[168:171], v[184:187], v[114:117]
	v_mfma_f32_16x16x32_bf16 v[106:109], v[176:179], v[184:187], v[106:109]
	v_mfma_f32_16x16x32_bf16 v[98:101], v[168:171], v[192:195], v[98:101]
	v_mfma_f32_16x16x32_bf16 v[90:93], v[176:179], v[192:195], v[90:93]
	v_mfma_f32_16x16x32_bf16 v[82:85], v[168:171], v[206:209], v[82:85]
	v_mfma_f32_16x16x32_bf16 v[74:77], v[176:179], v[206:209], v[74:77]
	v_mfma_f32_16x16x32_bf16 v[70:73], v[168:171], v[214:217], v[70:73]
	v_mfma_f32_16x16x32_bf16 v[66:69], v[176:179], v[214:217], v[66:69]
	s_barrier
	s_setprio 0
	s_add_i32 s1, s72, s26
	s_add_u32 s98, s8, s16
	s_addc_u32 s99, s9, s17
	s_mov_b32 m0, s1
	ds_read_b128 v[180:183], v151 offset:16384
	ds_read_b128 v[184:187], v151 offset:17408
	ds_read_b128 v[188:191], v151 offset:18432
	ds_read_b128 v[192:195], v151 offset:19456
	ds_read_b128 v[202:205], v151 offset:20480
	ds_read_b128 v[206:209], v151 offset:21504
	ds_read_b128 v[210:213], v151 offset:22528
	ds_read_b128 v[214:217], v151 offset:23552
	global_load_lds_dwordx4 v196, s[8:9]
	s_add_i32 m0, s1, 0x2000
	s_add_u32 s72, s8, 0x80000
	s_addc_u32 s73, s9, 0
	s_add_i32 s0, s0, s26
	global_load_lds_dwordx4 v130, s[8:9]
	s_mov_b32 m0, s0
	s_nop 0
	global_load_lds_dwordx4 v196, s[72:73]
	s_add_i32 m0, s0, 0x2000
	s_nop 0
	global_load_lds_dwordx4 v130, s[72:73]
	s_add_u32 s78, s62, s16
	s_addc_u32 s79, s63, s17
	s_mov_b32 m0, s27
	s_nop 0
	global_load_lds_dwordx4 v134, s[62:63]
	s_mov_b32 m0, s28
	s_nop 0
	global_load_lds_dwordx4 v132, s[62:63]
	s_waitcnt vmcnt(8)
	s_waitcnt lgkmcnt(0)
	s_setprio 1
	s_barrier
	v_mfma_f32_16x16x32_bf16 v[62:65], v[142:145], v[180:183], 0
	v_mfma_f32_16x16x32_bf16 v[58:61], v[156:159], v[180:183], 0
	v_mfma_f32_16x16x32_bf16 v[54:57], v[142:145], v[188:191], 0
	v_mfma_f32_16x16x32_bf16 v[46:49], v[156:159], v[188:191], 0
	v_mfma_f32_16x16x32_bf16 v[38:41], v[142:145], v[202:205], 0
	v_mfma_f32_16x16x32_bf16 v[30:33], v[156:159], v[202:205], 0
	v_mfma_f32_16x16x32_bf16 v[22:25], v[142:145], v[210:213], 0
	v_mfma_f32_16x16x32_bf16 v[14:17], v[156:159], v[210:213], 0
	v_mfma_f32_16x16x32_bf16 v[62:65], v[152:155], v[184:187], v[62:65]
	v_mfma_f32_16x16x32_bf16 v[58:61], v[160:163], v[184:187], v[58:61]
	v_mfma_f32_16x16x32_bf16 v[54:57], v[152:155], v[192:195], v[54:57]
	v_mfma_f32_16x16x32_bf16 v[46:49], v[160:163], v[192:195], v[46:49]
	v_mfma_f32_16x16x32_bf16 v[38:41], v[152:155], v[206:209], v[38:41]
	v_mfma_f32_16x16x32_bf16 v[30:33], v[160:163], v[206:209], v[30:33]
	v_mfma_f32_16x16x32_bf16 v[22:25], v[152:155], v[214:217], v[22:25]
	v_mfma_f32_16x16x32_bf16 v[14:17], v[160:163], v[214:217], v[14:17]
	v_mfma_f32_16x16x32_bf16 v[50:53], v[164:167], v[180:183], 0
	v_mfma_f32_16x16x32_bf16 v[42:45], v[172:175], v[180:183], 0
	v_mfma_f32_16x16x32_bf16 v[34:37], v[164:167], v[188:191], 0
	v_mfma_f32_16x16x32_bf16 v[26:29], v[172:175], v[188:191], 0
	v_mfma_f32_16x16x32_bf16 v[18:21], v[164:167], v[202:205], 0
	v_mfma_f32_16x16x32_bf16 v[10:13], v[172:175], v[202:205], 0
	v_mfma_f32_16x16x32_bf16 v[6:9], v[164:167], v[210:213], 0
	v_mfma_f32_16x16x32_bf16 v[2:5], v[172:175], v[210:213], 0
	v_mfma_f32_16x16x32_bf16 v[50:53], v[168:171], v[184:187], v[50:53]
	v_mfma_f32_16x16x32_bf16 v[42:45], v[176:179], v[184:187], v[42:45]
	v_mfma_f32_16x16x32_bf16 v[34:37], v[168:171], v[192:195], v[34:37]
	v_mfma_f32_16x16x32_bf16 v[26:29], v[176:179], v[192:195], v[26:29]
	v_mfma_f32_16x16x32_bf16 v[18:21], v[168:171], v[206:209], v[18:21]
	v_mfma_f32_16x16x32_bf16 v[10:13], v[176:179], v[206:209], v[10:13]
	v_mfma_f32_16x16x32_bf16 v[6:9], v[168:171], v[214:217], v[6:9]
	v_mfma_f32_16x16x32_bf16 v[2:5], v[176:179], v[214:217], v[2:5]
	s_barrier
	s_setprio 0
	s_branch .Lkmid_2

.Lkmid_2:
	s_add_i32 s0, 0, 0x18000
	s_add_i32 s1, 0, 0x1c000
	v_add_u32_e32 v160, s0, v149
	v_add_u32_e32 v176, s1, v149
	ds_read_b128 v[142:145], v160
	ds_read_b128 v[152:155], v160 offset:1024
	ds_read_b128 v[156:159], v160 offset:2048
	ds_read_b128 v[160:163], v160 offset:3072
	ds_read_b128 v[164:167], v176
	ds_read_b128 v[168:171], v176 offset:1024
	ds_read_b128 v[172:175], v176 offset:2048
	ds_read_b128 v[176:179], v176 offset:3072
	s_add_u32 s62, s62, 0x80000
	s_addc_u32 s63, s63, 0
	s_mov_b32 m0, s29
	ds_read_b128 v[180:183], v151 offset:32768
	ds_read_b128 v[184:187], v151 offset:33792
	ds_read_b128 v[188:191], v151 offset:34816
	ds_read_b128 v[192:195], v151 offset:35840
	ds_read_b128 v[202:205], v151 offset:36864
	ds_read_b128 v[206:209], v151 offset:37888
	ds_read_b128 v[210:213], v151 offset:38912
	ds_read_b128 v[214:217], v151 offset:39936
	global_load_lds_dwordx4 v134, s[62:63]
	s_mov_b32 m0, s30
	s_nop 0
	global_load_lds_dwordx4 v132, s[62:63]
	s_waitcnt vmcnt(8)
	s_waitcnt lgkmcnt(0)
	s_setprio 1
	s_barrier
	v_mfma_f32_16x16x32_bf16 v[126:129], v[142:145], v[180:183], v[126:129]
	v_mfma_f32_16x16x32_bf16 v[122:125], v[156:159], v[180:183], v[122:125]
	v_mfma_f32_16x16x32_bf16 v[118:121], v[142:145], v[188:191], v[118:121]
	v_mfma_f32_16x16x32_bf16 v[110:113], v[156:159], v[188:191], v[110:113]
	v_mfma_f32_16x16x32_bf16 v[102:105], v[142:145], v[202:205], v[102:105]
	v_mfma_f32_16x16x32_bf16 v[94:97], v[156:159], v[202:205], v[94:97]
	v_mfma_f32_16x16x32_bf16 v[86:89], v[142:145], v[210:213], v[86:89]
	v_mfma_f32_16x16x32_bf16 v[78:81], v[156:159], v[210:213], v[78:81]
	v_mfma_f32_16x16x32_bf16 v[126:129], v[152:155], v[184:187], v[126:129]
	v_mfma_f32_16x16x32_bf16 v[122:125], v[160:163], v[184:187], v[122:125]
	v_mfma_f32_16x16x32_bf16 v[118:121], v[152:155], v[192:195], v[118:121]
	v_mfma_f32_16x16x32_bf16 v[110:113], v[160:163], v[192:195], v[110:113]
	v_mfma_f32_16x16x32_bf16 v[102:105], v[152:155], v[206:209], v[102:105]
	v_mfma_f32_16x16x32_bf16 v[94:97], v[160:163], v[206:209], v[94:97]
	v_mfma_f32_16x16x32_bf16 v[86:89], v[152:155], v[214:217], v[86:89]
	v_mfma_f32_16x16x32_bf16 v[78:81], v[160:163], v[214:217], v[78:81]
	v_mfma_f32_16x16x32_bf16 v[114:117], v[164:167], v[180:183], v[114:117]
	v_mfma_f32_16x16x32_bf16 v[106:109], v[172:175], v[180:183], v[106:109]
	v_mfma_f32_16x16x32_bf16 v[98:101], v[164:167], v[188:191], v[98:101]
	v_mfma_f32_16x16x32_bf16 v[90:93], v[172:175], v[188:191], v[90:93]
	v_mfma_f32_16x16x32_bf16 v[82:85], v[164:167], v[202:205], v[82:85]
	v_mfma_f32_16x16x32_bf16 v[74:77], v[172:175], v[202:205], v[74:77]
	v_mfma_f32_16x16x32_bf16 v[70:73], v[164:167], v[210:213], v[70:73]
	v_mfma_f32_16x16x32_bf16 v[66:69], v[172:175], v[210:213], v[66:69]
	v_mfma_f32_16x16x32_bf16 v[114:117], v[168:171], v[184:187], v[114:117]
	v_mfma_f32_16x16x32_bf16 v[106:109], v[176:179], v[184:187], v[106:109]
	v_mfma_f32_16x16x32_bf16 v[98:101], v[168:171], v[192:195], v[98:101]
	v_mfma_f32_16x16x32_bf16 v[90:93], v[176:179], v[192:195], v[90:93]
	v_mfma_f32_16x16x32_bf16 v[82:85], v[168:171], v[206:209], v[82:85]
	v_mfma_f32_16x16x32_bf16 v[74:77], v[176:179], v[206:209], v[74:77]
	v_mfma_f32_16x16x32_bf16 v[70:73], v[168:171], v[214:217], v[70:73]
	v_mfma_f32_16x16x32_bf16 v[66:69], v[176:179], v[214:217], v[66:69]
	s_barrier
	s_setprio 0
	s_add_i32 s0, s0, s26
	s_mov_b32 m0, s0
	ds_read_b128 v[180:183], v151 offset:49152
	ds_read_b128 v[184:187], v151 offset:50176
	ds_read_b128 v[188:191], v151 offset:51200
	ds_read_b128 v[192:195], v151 offset:52224
	ds_read_b128 v[202:205], v151 offset:53248
	ds_read_b128 v[206:209], v151 offset:54272
	ds_read_b128 v[210:213], v151 offset:55296
	ds_read_b128 v[214:217], v151 offset:56320
	global_load_lds_dwordx4 v196, s[98:99]
	s_add_i32 m0, s0, 0x2000
	s_add_u32 s8, s8, 0x80080
	s_addc_u32 s9, s9, 0
	s_add_i32 s0, s1, s26
	global_load_lds_dwordx4 v130, s[98:99]
	s_mov_b32 m0, s0
	s_nop 0
	global_load_lds_dwordx4 v196, s[8:9]
	s_add_i32 m0, s0, 0x2000
	s_nop 0
	global_load_lds_dwordx4 v130, s[8:9]
	s_mov_b32 m0, s31
	s_nop 0
	global_load_lds_dwordx4 v134, s[78:79]
	s_mov_b32 m0, s34
	s_nop 0
	global_load_lds_dwordx4 v132, s[78:79]
	s_waitcnt vmcnt(8)
	s_waitcnt lgkmcnt(0)
	s_setprio 1
	s_barrier
	v_mfma_f32_16x16x32_bf16 v[62:65], v[142:145], v[180:183], v[62:65]
	v_mfma_f32_16x16x32_bf16 v[58:61], v[156:159], v[180:183], v[58:61]
	v_mfma_f32_16x16x32_bf16 v[54:57], v[142:145], v[188:191], v[54:57]
	v_mfma_f32_16x16x32_bf16 v[46:49], v[156:159], v[188:191], v[46:49]
	v_mfma_f32_16x16x32_bf16 v[38:41], v[142:145], v[202:205], v[38:41]
	v_mfma_f32_16x16x32_bf16 v[30:33], v[156:159], v[202:205], v[30:33]
	v_mfma_f32_16x16x32_bf16 v[22:25], v[142:145], v[210:213], v[22:25]
	v_mfma_f32_16x16x32_bf16 v[14:17], v[156:159], v[210:213], v[14:17]
	v_mfma_f32_16x16x32_bf16 v[62:65], v[152:155], v[184:187], v[62:65]
	v_mfma_f32_16x16x32_bf16 v[58:61], v[160:163], v[184:187], v[58:61]
	v_mfma_f32_16x16x32_bf16 v[54:57], v[152:155], v[192:195], v[54:57]
	v_mfma_f32_16x16x32_bf16 v[46:49], v[160:163], v[192:195], v[46:49]
	v_mfma_f32_16x16x32_bf16 v[38:41], v[152:155], v[206:209], v[38:41]
	v_mfma_f32_16x16x32_bf16 v[30:33], v[160:163], v[206:209], v[30:33]
	v_mfma_f32_16x16x32_bf16 v[22:25], v[152:155], v[214:217], v[22:25]
	v_mfma_f32_16x16x32_bf16 v[14:17], v[160:163], v[214:217], v[14:17]
	v_mfma_f32_16x16x32_bf16 v[50:53], v[164:167], v[180:183], v[50:53]
	v_mfma_f32_16x16x32_bf16 v[42:45], v[172:175], v[180:183], v[42:45]
	v_mfma_f32_16x16x32_bf16 v[34:37], v[164:167], v[188:191], v[34:37]
	v_mfma_f32_16x16x32_bf16 v[26:29], v[172:175], v[188:191], v[26:29]
	v_mfma_f32_16x16x32_bf16 v[18:21], v[164:167], v[202:205], v[18:21]
	v_mfma_f32_16x16x32_bf16 v[10:13], v[172:175], v[202:205], v[10:13]
	v_mfma_f32_16x16x32_bf16 v[6:9], v[164:167], v[210:213], v[6:9]
	v_mfma_f32_16x16x32_bf16 v[2:5], v[172:175], v[210:213], v[2:5]
	v_mfma_f32_16x16x32_bf16 v[50:53], v[168:171], v[184:187], v[50:53]
	v_mfma_f32_16x16x32_bf16 v[42:45], v[176:179], v[184:187], v[42:45]
	v_mfma_f32_16x16x32_bf16 v[34:37], v[168:171], v[192:195], v[34:37]
	v_mfma_f32_16x16x32_bf16 v[26:29], v[176:179], v[192:195], v[26:29]
	v_mfma_f32_16x16x32_bf16 v[18:21], v[168:171], v[206:209], v[18:21]
	v_mfma_f32_16x16x32_bf16 v[10:13], v[176:179], v[206:209], v[10:13]
	v_mfma_f32_16x16x32_bf16 v[6:9], v[168:171], v[214:217], v[6:9]
	v_mfma_f32_16x16x32_bf16 v[2:5], v[176:179], v[214:217], v[2:5]
	s_barrier
	s_setprio 0
	s_add_u32 s69, s69, 0x100
	s_addc_u32 s70, s70, 0
	s_add_u32 s58, s58, 0x100
	s_addc_u32 s59, s59, 0
	s_cmp_ge_i32 s71, s64
	s_mov_b32 s8, s71
	s_cbranch_scc0 .LBB0_1135
	s_and_b64 vcc, exec, s[38:39]
	s_cbranch_vccz .LBB0_1138
	s_barrier

.LBB0_2238:
	s_ashr_i32 s53, s52, 31
	s_lshl_b64 s[0:1], s[52:53], 21
	s_add_u32 s49, s38, s0
	s_addc_u32 s53, s39, s1
	s_ashr_i32 s51, s50, 31
	s_lshl_b64 s[0:1], s[50:51], 1
	s_add_u32 s62, s49, s0
	s_addc_u32 s63, s53, s1
	s_and_b64 s[64:65], s[58:59], exec
	s_cselect_b32 s51, s63, s9
	s_cselect_b32 s53, s62, s8
	s_ashr_i32 s49, s48, 31
	s_lshl_b64 s[64:65], s[48:49], 21
	s_add_u32 s49, s40, s64
	s_addc_u32 s65, s41, s65
	s_add_u32 s64, s49, s0
	s_addc_u32 s65, s65, s1
	s_and_b64 s[0:1], s[58:59], exec
	s_cselect_b32 s49, s65, s45
	s_cselect_b32 s69, s64, s44
	s_add_i32 s70, s35, -2
	s_add_u32 s71, s44, 0x100
	s_addc_u32 s72, s45, 0
	s_add_u32 s44, s8, 0x100080
	s_addc_u32 s45, s9, 0
	s_mov_b32 s8, 0
	s_nop 0
	s_cmp_eq_u32 s100, 1
	s_cbranch_scc0 .Ldefbar_skip_3
	s_mov_b32 s100, 0
	s_barrier
.Ldefbar_skip_3:
	s_add_i32 s73, s8, 2
	s_add_u32 s0, s44, 0xfff00080
	s_addc_u32 s1, s45, -1
	s_add_i32 s77, 0, 0x10000
	s_cmp_eq_u32 s70, s8
	s_cselect_b32 s67, s51, s1
	s_cselect_b32 s66, s53, s0
	s_cselect_b32 s9, s49, s72
	s_cselect_b32 s8, s69, s71
	s_add_i32 s78, 0, 0x14000
	v_add_u32_e32 v142, s77, v244
	v_add_u32_e32 v158, s78, v244
	ds_read_b128 v[130:133], v142
	ds_read_b128 v[134:137], v142 offset:1024
	ds_read_b128 v[138:141], v142 offset:2048
	ds_read_b128 v[142:145], v142 offset:3072
	ds_read_b128 v[146:149], v158
	ds_read_b128 v[150:153], v158 offset:1024
	ds_read_b128 v[154:157], v158 offset:2048
	ds_read_b128 v[158:161], v158 offset:3072
	s_add_i32 m0, s3, 0xc000
	ds_read_b128 v[162:165], v246
	ds_read_b128 v[166:169], v246 offset:1024
	ds_read_b128 v[170:173], v246 offset:2048
	ds_read_b128 v[174:177], v246 offset:3072
	ds_read_b128 v[178:181], v246 offset:4096
	ds_read_b128 v[182:185], v246 offset:5120
	ds_read_b128 v[186:189], v246 offset:6144
	ds_read_b128 v[190:193], v246 offset:7168
	global_load_lds_dwordx4 v210, s[44:45]
	s_add_i32 m0, s3, 0xe000
	s_nop 0
	global_load_lds_dwordx4 v208, s[44:45]
	s_waitcnt vmcnt(8)
	s_waitcnt lgkmcnt(0)
	s_setprio 1
	s_barrier
	v_mfma_f32_16x16x32_bf16 v[126:129], v[130:133], v[162:165], 0
	v_mfma_f32_16x16x32_bf16 v[122:125], v[138:141], v[162:165], 0
	v_mfma_f32_16x16x32_bf16 v[110:113], v[130:133], v[170:173], 0
	v_mfma_f32_16x16x32_bf16 v[106:109], v[138:141], v[170:173], 0
	v_mfma_f32_16x16x32_bf16 v[94:97], v[130:133], v[178:181], 0
	v_mfma_f32_16x16x32_bf16 v[90:93], v[138:141], v[178:181], 0
	v_mfma_f32_16x16x32_bf16 v[78:81], v[130:133], v[186:189], 0
	v_mfma_f32_16x16x32_bf16 v[74:77], v[138:141], v[186:189], 0
	v_mfma_f32_16x16x32_bf16 v[126:129], v[134:137], v[166:169], v[126:129]
	v_mfma_f32_16x16x32_bf16 v[122:125], v[142:145], v[166:169], v[122:125]
	v_mfma_f32_16x16x32_bf16 v[110:113], v[134:137], v[174:177], v[110:113]
	v_mfma_f32_16x16x32_bf16 v[106:109], v[142:145], v[174:177], v[106:109]
	v_mfma_f32_16x16x32_bf16 v[94:97], v[134:137], v[182:185], v[94:97]
	v_mfma_f32_16x16x32_bf16 v[90:93], v[142:145], v[182:185], v[90:93]
	v_mfma_f32_16x16x32_bf16 v[78:81], v[134:137], v[190:193], v[78:81]
	v_mfma_f32_16x16x32_bf16 v[74:77], v[142:145], v[190:193], v[74:77]
	v_mfma_f32_16x16x32_bf16 v[118:121], v[146:149], v[162:165], 0
	v_mfma_f32_16x16x32_bf16 v[114:117], v[154:157], v[162:165], 0
	v_mfma_f32_16x16x32_bf16 v[102:105], v[146:149], v[170:173], 0
	v_mfma_f32_16x16x32_bf16 v[98:101], v[154:157], v[170:173], 0
	v_mfma_f32_16x16x32_bf16 v[86:89], v[146:149], v[178:181], 0
	v_mfma_f32_16x16x32_bf16 v[82:85], v[154:157], v[178:181], 0
	v_mfma_f32_16x16x32_bf16 v[70:73], v[146:149], v[186:189], 0
	v_mfma_f32_16x16x32_bf16 v[66:69], v[154:157], v[186:189], 0
	v_mfma_f32_16x16x32_bf16 v[118:121], v[150:153], v[166:169], v[118:121]
	v_mfma_f32_16x16x32_bf16 v[114:117], v[158:161], v[166:169], v[114:117]
	v_mfma_f32_16x16x32_bf16 v[102:105], v[150:153], v[174:177], v[102:105]
	v_mfma_f32_16x16x32_bf16 v[98:101], v[158:161], v[174:177], v[98:101]
	v_mfma_f32_16x16x32_bf16 v[86:89], v[150:153], v[182:185], v[86:89]
	v_mfma_f32_16x16x32_bf16 v[82:85], v[158:161], v[182:185], v[82:85]
	v_mfma_f32_16x16x32_bf16 v[70:73], v[150:153], v[190:193], v[70:73]
	v_mfma_f32_16x16x32_bf16 v[66:69], v[158:161], v[190:193], v[66:69]
	s_barrier
	s_setprio 0
	s_add_i32 s0, s77, s2
	s_add_u32 s98, s8, s16
	s_addc_u32 s99, s9, s17
	s_mov_b32 m0, s0
	ds_read_b128 v[162:165], v246 offset:16384
	ds_read_b128 v[166:169], v246 offset:17408
	ds_read_b128 v[170:173], v246 offset:18432
	ds_read_b128 v[174:177], v246 offset:19456
	ds_read_b128 v[178:181], v246 offset:20480
	ds_read_b128 v[182:185], v246 offset:21504
	ds_read_b128 v[186:189], v246 offset:22528
	ds_read_b128 v[190:193], v246 offset:23552
	global_load_lds_dwordx4 v196, s[8:9]
	s_add_i32 m0, s0, 0x2000
	s_add_u32 s0, s8, 0x100000
	s_addc_u32 s1, s9, 0
	s_add_i32 s77, s78, s2
	global_load_lds_dwordx4 v202, s[8:9]
	s_mov_b32 m0, s77
	v_lshl_add_u64 v[216:217], s[66:67], 0, v[204:205]
	global_load_lds_dwordx4 v196, s[0:1]
	s_add_i32 m0, s77, 0x2000
	s_nop 0
	global_load_lds_dwordx4 v202, s[0:1]
	v_lshl_add_u64 v[214:215], s[66:67], 0, v[206:207]
	s_mov_b32 m0, s3
	s_nop 0
	global_load_lds_dwordx4 v206, s[66:67]
	s_mov_b32 m0, s10
	s_nop 0
	global_load_lds_dwordx4 v204, s[66:67]
	s_waitcnt vmcnt(8)
	s_waitcnt lgkmcnt(0)
	s_setprio 1
	s_barrier
	v_mfma_f32_16x16x32_bf16 v[62:65], v[130:133], v[162:165], 0
	v_mfma_f32_16x16x32_bf16 v[58:61], v[138:141], v[162:165], 0
	v_mfma_f32_16x16x32_bf16 v[46:49], v[130:133], v[170:173], 0
	v_mfma_f32_16x16x32_bf16 v[42:45], v[138:141], v[170:173], 0
	v_mfma_f32_16x16x32_bf16 v[30:33], v[130:133], v[178:181], 0
	v_mfma_f32_16x16x32_bf16 v[26:29], v[138:141], v[178:181], 0
	v_mfma_f32_16x16x32_bf16 v[14:17], v[130:133], v[186:189], 0
	v_mfma_f32_16x16x32_bf16 v[10:13], v[138:141], v[186:189], 0
	v_mfma_f32_16x16x32_bf16 v[62:65], v[134:137], v[166:169], v[62:65]
	v_mfma_f32_16x16x32_bf16 v[58:61], v[142:145], v[166:169], v[58:61]
	v_mfma_f32_16x16x32_bf16 v[46:49], v[134:137], v[174:177], v[46:49]
	v_mfma_f32_16x16x32_bf16 v[42:45], v[142:145], v[174:177], v[42:45]
	v_mfma_f32_16x16x32_bf16 v[30:33], v[134:137], v[182:185], v[30:33]
	v_mfma_f32_16x16x32_bf16 v[26:29], v[142:145], v[182:185], v[26:29]
	v_mfma_f32_16x16x32_bf16 v[14:17], v[134:137], v[190:193], v[14:17]
	v_mfma_f32_16x16x32_bf16 v[10:13], v[142:145], v[190:193], v[10:13]
	v_mfma_f32_16x16x32_bf16 v[54:57], v[146:149], v[162:165], 0
	v_mfma_f32_16x16x32_bf16 v[50:53], v[154:157], v[162:165], 0
	v_mfma_f32_16x16x32_bf16 v[38:41], v[146:149], v[170:173], 0
	v_mfma_f32_16x16x32_bf16 v[34:37], v[154:157], v[170:173], 0
	v_mfma_f32_16x16x32_bf16 v[22:25], v[146:149], v[178:181], 0
	v_mfma_f32_16x16x32_bf16 v[18:21], v[154:157], v[178:181], 0
	v_mfma_f32_16x16x32_bf16 v[6:9], v[146:149], v[186:189], 0
	v_mfma_f32_16x16x32_bf16 v[2:5], v[154:157], v[186:189], 0
	v_mfma_f32_16x16x32_bf16 v[54:57], v[150:153], v[166:169], v[54:57]
	v_mfma_f32_16x16x32_bf16 v[50:53], v[158:161], v[166:169], v[50:53]
	v_mfma_f32_16x16x32_bf16 v[38:41], v[150:153], v[174:177], v[38:41]
	v_mfma_f32_16x16x32_bf16 v[34:37], v[158:161], v[174:177], v[34:37]
	v_mfma_f32_16x16x32_bf16 v[22:25], v[150:153], v[182:185], v[22:25]
	v_mfma_f32_16x16x32_bf16 v[18:21], v[158:161], v[182:185], v[18:21]
	v_mfma_f32_16x16x32_bf16 v[6:9], v[150:153], v[190:193], v[6:9]
	v_mfma_f32_16x16x32_bf16 v[2:5], v[158:161], v[190:193], v[2:5]
	s_barrier
	s_setprio 0
	s_branch .Lkmid_3

.Lkmid_3:
	s_add_i32 s77, 0, 0x18000
	s_add_i32 s78, 0, 0x1c000
	v_add_u32_e32 v142, s77, v244
	v_add_u32_e32 v158, s78, v244
	ds_read_b128 v[130:133], v142
	ds_read_b128 v[134:137], v142 offset:1024
	ds_read_b128 v[138:141], v142 offset:2048
	ds_read_b128 v[142:145], v142 offset:3072
	ds_read_b128 v[146:149], v158
	ds_read_b128 v[150:153], v158 offset:1024
	ds_read_b128 v[154:157], v158 offset:2048
	ds_read_b128 v[158:161], v158 offset:3072
	s_add_u32 s0, s66, 0x100000
	s_addc_u32 s1, s67, 0
	s_mov_b32 m0, s11
	ds_read_b128 v[162:165], v246 offset:32768
	ds_read_b128 v[166:169], v246 offset:33792
	ds_read_b128 v[170:173], v246 offset:34816
	ds_read_b128 v[174:177], v246 offset:35840
	ds_read_b128 v[178:181], v246 offset:36864
	ds_read_b128 v[182:185], v246 offset:37888
	ds_read_b128 v[186:189], v246 offset:38912
	ds_read_b128 v[190:193], v246 offset:39936
	global_load_lds_dwordx4 v206, s[0:1]
	s_mov_b32 m0, s26
	s_nop 0
	global_load_lds_dwordx4 v204, s[0:1]
	s_waitcnt vmcnt(8)
	s_waitcnt lgkmcnt(0)
	s_setprio 1
	s_barrier
	v_mfma_f32_16x16x32_bf16 v[126:129], v[130:133], v[162:165], v[126:129]
	v_mfma_f32_16x16x32_bf16 v[122:125], v[138:141], v[162:165], v[122:125]
	v_mfma_f32_16x16x32_bf16 v[110:113], v[130:133], v[170:173], v[110:113]
	v_mfma_f32_16x16x32_bf16 v[106:109], v[138:141], v[170:173], v[106:109]
	v_mfma_f32_16x16x32_bf16 v[94:97], v[130:133], v[178:181], v[94:97]
	v_mfma_f32_16x16x32_bf16 v[90:93], v[138:141], v[178:181], v[90:93]
	v_mfma_f32_16x16x32_bf16 v[78:81], v[130:133], v[186:189], v[78:81]
	v_mfma_f32_16x16x32_bf16 v[74:77], v[138:141], v[186:189], v[74:77]
	v_mfma_f32_16x16x32_bf16 v[126:129], v[134:137], v[166:169], v[126:129]
	v_mfma_f32_16x16x32_bf16 v[122:125], v[142:145], v[166:169], v[122:125]
	v_mfma_f32_16x16x32_bf16 v[110:113], v[134:137], v[174:177], v[110:113]
	v_mfma_f32_16x16x32_bf16 v[106:109], v[142:145], v[174:177], v[106:109]
	v_mfma_f32_16x16x32_bf16 v[94:97], v[134:137], v[182:185], v[94:97]
	v_mfma_f32_16x16x32_bf16 v[90:93], v[142:145], v[182:185], v[90:93]
	v_mfma_f32_16x16x32_bf16 v[78:81], v[134:137], v[190:193], v[78:81]
	v_mfma_f32_16x16x32_bf16 v[74:77], v[142:145], v[190:193], v[74:77]
	v_mfma_f32_16x16x32_bf16 v[118:121], v[146:149], v[162:165], v[118:121]
	v_mfma_f32_16x16x32_bf16 v[114:117], v[154:157], v[162:165], v[114:117]
	v_mfma_f32_16x16x32_bf16 v[102:105], v[146:149], v[170:173], v[102:105]
	v_mfma_f32_16x16x32_bf16 v[98:101], v[154:157], v[170:173], v[98:101]
	v_mfma_f32_16x16x32_bf16 v[86:89], v[146:149], v[178:181], v[86:89]
	v_mfma_f32_16x16x32_bf16 v[82:85], v[154:157], v[178:181], v[82:85]
	v_mfma_f32_16x16x32_bf16 v[70:73], v[146:149], v[186:189], v[70:73]
	v_mfma_f32_16x16x32_bf16 v[66:69], v[154:157], v[186:189], v[66:69]
	v_mfma_f32_16x16x32_bf16 v[118:121], v[150:153], v[166:169], v[118:121]
	v_mfma_f32_16x16x32_bf16 v[114:117], v[158:161], v[166:169], v[114:117]
	v_mfma_f32_16x16x32_bf16 v[102:105], v[150:153], v[174:177], v[102:105]
	v_mfma_f32_16x16x32_bf16 v[98:101], v[158:161], v[174:177], v[98:101]
	v_mfma_f32_16x16x32_bf16 v[86:89], v[150:153], v[182:185], v[86:89]
	v_mfma_f32_16x16x32_bf16 v[82:85], v[158:161], v[182:185], v[82:85]
	v_mfma_f32_16x16x32_bf16 v[70:73], v[150:153], v[190:193], v[70:73]
	v_mfma_f32_16x16x32_bf16 v[66:69], v[158:161], v[190:193], v[66:69]
	s_barrier
	s_setprio 0
	s_add_i32 s0, s77, s2
	s_mov_b32 m0, s0
	ds_read_b128 v[162:165], v246 offset:49152
	ds_read_b128 v[166:169], v246 offset:50176
	ds_read_b128 v[170:173], v246 offset:51200
	ds_read_b128 v[174:177], v246 offset:52224
	ds_read_b128 v[178:181], v246 offset:53248
	ds_read_b128 v[182:185], v246 offset:54272
	ds_read_b128 v[186:189], v246 offset:55296
	ds_read_b128 v[190:193], v246 offset:56320
	global_load_lds_dwordx4 v196, s[98:99]
	s_add_i32 m0, s0, 0x2000
	s_add_u32 s0, s8, 0x100080
	s_addc_u32 s1, s9, 0
	s_add_i32 s8, s78, s2
	global_load_lds_dwordx4 v202, s[98:99]
	s_mov_b32 m0, s8
	s_nop 0
	global_load_lds_dwordx4 v196, s[0:1]
	s_add_i32 m0, s8, 0x2000
	s_nop 0
	global_load_lds_dwordx4 v202, s[0:1]
	v_lshl_add_u64 v[194:195], v[214:215], 0, s[16:17]
	s_mov_b32 m0, s27
	s_nop 0
	global_load_lds_dwordx4 v[194:195], off
	v_lshl_add_u64 v[194:195], v[216:217], 0, s[16:17]
	s_mov_b32 m0, s28
	s_nop 0
	global_load_lds_dwordx4 v[194:195], off
	s_waitcnt vmcnt(8)
	s_waitcnt lgkmcnt(0)
	s_setprio 1
	s_barrier
	v_mfma_f32_16x16x32_bf16 v[62:65], v[130:133], v[162:165], v[62:65]
	v_mfma_f32_16x16x32_bf16 v[58:61], v[138:141], v[162:165], v[58:61]
	v_mfma_f32_16x16x32_bf16 v[46:49], v[130:133], v[170:173], v[46:49]
	v_mfma_f32_16x16x32_bf16 v[42:45], v[138:141], v[170:173], v[42:45]
	v_mfma_f32_16x16x32_bf16 v[30:33], v[130:133], v[178:181], v[30:33]
	v_mfma_f32_16x16x32_bf16 v[26:29], v[138:141], v[178:181], v[26:29]
	v_mfma_f32_16x16x32_bf16 v[14:17], v[130:133], v[186:189], v[14:17]
	v_mfma_f32_16x16x32_bf16 v[10:13], v[138:141], v[186:189], v[10:13]
	v_mfma_f32_16x16x32_bf16 v[62:65], v[134:137], v[166:169], v[62:65]
	v_mfma_f32_16x16x32_bf16 v[58:61], v[142:145], v[166:169], v[58:61]
	v_mfma_f32_16x16x32_bf16 v[46:49], v[134:137], v[174:177], v[46:49]
	v_mfma_f32_16x16x32_bf16 v[42:45], v[142:145], v[174:177], v[42:45]
	v_mfma_f32_16x16x32_bf16 v[30:33], v[134:137], v[182:185], v[30:33]
	v_mfma_f32_16x16x32_bf16 v[26:29], v[142:145], v[182:185], v[26:29]
	v_mfma_f32_16x16x32_bf16 v[14:17], v[134:137], v[190:193], v[14:17]
	v_mfma_f32_16x16x32_bf16 v[10:13], v[142:145], v[190:193], v[10:13]
	v_mfma_f32_16x16x32_bf16 v[54:57], v[146:149], v[162:165], v[54:57]
	v_mfma_f32_16x16x32_bf16 v[50:53], v[154:157], v[162:165], v[50:53]
	v_mfma_f32_16x16x32_bf16 v[38:41], v[146:149], v[170:173], v[38:41]
	v_mfma_f32_16x16x32_bf16 v[34:37], v[154:157], v[170:173], v[34:37]
	v_mfma_f32_16x16x32_bf16 v[22:25], v[146:149], v[178:181], v[22:25]
	v_mfma_f32_16x16x32_bf16 v[18:21], v[154:157], v[178:181], v[18:21]
	v_mfma_f32_16x16x32_bf16 v[6:9], v[146:149], v[186:189], v[6:9]
	v_mfma_f32_16x16x32_bf16 v[2:5], v[154:157], v[186:189], v[2:5]
	v_mfma_f32_16x16x32_bf16 v[54:57], v[150:153], v[166:169], v[54:57]
	v_mfma_f32_16x16x32_bf16 v[50:53], v[158:161], v[166:169], v[50:53]
	v_mfma_f32_16x16x32_bf16 v[38:41], v[150:153], v[174:177], v[38:41]
	v_mfma_f32_16x16x32_bf16 v[34:37], v[158:161], v[174:177], v[34:37]
	v_mfma_f32_16x16x32_bf16 v[22:25], v[150:153], v[182:185], v[22:25]
	v_mfma_f32_16x16x32_bf16 v[18:21], v[158:161], v[182:185], v[18:21]
	v_mfma_f32_16x16x32_bf16 v[6:9], v[150:153], v[190:193], v[6:9]
	v_mfma_f32_16x16x32_bf16 v[2:5], v[158:161], v[190:193], v[2:5]
	s_barrier
	s_setprio 0
	s_add_u32 s71, s71, 0x100
	s_addc_u32 s72, s72, 0
	s_add_u32 s44, s44, 0x100
	s_addc_u32 s45, s45, 0
	s_cmp_ge_i32 s73, s35
	s_mov_b32 s8, s73
	s_cbranch_scc0 .LBB0_2239
	s_and_b64 vcc, exec, s[46:47]
	s_cbranch_vccz .LBB0_2242
	s_barrier

.LBB0_2356:
	s_ashr_i32 s45, s44, 31
	s_lshl_b64 s[0:1], s[44:45], 20
	s_add_u32 s43, s2, s0
	s_addc_u32 s45, s3, s1
	s_ashr_i32 s41, s40, 31
	s_lshl_b64 s[0:1], s[40:41], 1
	s_add_u32 s48, s43, s0
	s_addc_u32 s49, s45, s1
	s_and_b64 s[50:51], s[46:47], exec
	s_cselect_b32 s41, s49, s63
	s_cselect_b32 s45, s48, s62
	s_ashr_i32 s43, s42, 31
	s_lshl_b64 s[50:51], s[42:43], 20
	s_add_u32 s43, s10, s50
	s_addc_u32 s51, s11, s51
	s_add_u32 s50, s43, s0
	s_addc_u32 s51, s51, s1
	s_and_b64 s[0:1], s[46:47], exec
	s_cselect_b32 s43, s51, s9
	s_cselect_b32 s70, s50, s8
	s_add_i32 s71, s69, -2
	s_add_u32 s72, s8, 0x100
	s_addc_u32 s73, s9, 0
	s_add_u32 s62, s62, 0x80080
	s_addc_u32 s63, s63, 0
	s_mov_b32 s8, 0
	s_nop 0
	s_cmp_eq_u32 s100, 1
	s_cbranch_scc0 .Ldefbar_skip_4
	s_mov_b32 s100, 0
	s_barrier
.Ldefbar_skip_4:
	s_add_i32 s77, s8, 2
	s_add_u32 s0, s62, 0xfff80080
	s_addc_u32 s1, s63, -1
	s_add_i32 s78, 0, 0x10000
	s_cmp_eq_u32 s71, s8
	s_cselect_b32 s65, s41, s1
	s_cselect_b32 s64, s45, s0
	s_cselect_b32 s9, s43, s73
	s_cselect_b32 s8, s70, s72
	s_add_i32 s79, 0, 0x14000
	v_add_u32_e32 v142, s78, v188
	v_add_u32_e32 v158, s79, v188
	ds_read_b128 v[130:133], v142
	ds_read_b128 v[134:137], v142 offset:1024
	ds_read_b128 v[138:141], v142 offset:2048
	ds_read_b128 v[142:145], v142 offset:3072
	ds_read_b128 v[146:149], v158
	ds_read_b128 v[150:153], v158 offset:1024
	ds_read_b128 v[154:157], v158 offset:2048
	ds_read_b128 v[158:161], v158 offset:3072
	s_add_i32 m0, s27, 0xc000
	ds_read_b128 v[162:165], v189
	ds_read_b128 v[180:183], v189 offset:1024
	ds_read_b128 v[184:187], v189 offset:2048
	ds_read_b128 v[190:193], v189 offset:3072
	ds_read_b128 v[202:205], v189 offset:4096
	ds_read_b128 v[206:209], v189 offset:5120
	ds_read_b128 v[210:213], v189 offset:6144
	ds_read_b128 v[214:217], v189 offset:7168
	global_load_lds_dwordx4 v178, s[62:63]
	s_add_i32 m0, s27, 0xe000
	s_nop 0
	global_load_lds_dwordx4 v176, s[62:63]
	s_waitcnt vmcnt(8)
	s_waitcnt lgkmcnt(0)
	s_setprio 1
	s_barrier
	v_mfma_f32_16x16x32_bf16 v[126:129], v[130:133], v[162:165], 0
	v_mfma_f32_16x16x32_bf16 v[122:125], v[138:141], v[162:165], 0
	v_mfma_f32_16x16x32_bf16 v[110:113], v[130:133], v[184:187], 0
	v_mfma_f32_16x16x32_bf16 v[106:109], v[138:141], v[184:187], 0
	v_mfma_f32_16x16x32_bf16 v[98:101], v[130:133], v[202:205], 0
	v_mfma_f32_16x16x32_bf16 v[90:93], v[138:141], v[202:205], 0
	v_mfma_f32_16x16x32_bf16 v[82:85], v[130:133], v[210:213], 0
	v_mfma_f32_16x16x32_bf16 v[74:77], v[138:141], v[210:213], 0
	v_mfma_f32_16x16x32_bf16 v[126:129], v[134:137], v[180:183], v[126:129]
	v_mfma_f32_16x16x32_bf16 v[122:125], v[142:145], v[180:183], v[122:125]
	v_mfma_f32_16x16x32_bf16 v[110:113], v[134:137], v[190:193], v[110:113]
	v_mfma_f32_16x16x32_bf16 v[106:109], v[142:145], v[190:193], v[106:109]
	v_mfma_f32_16x16x32_bf16 v[98:101], v[134:137], v[206:209], v[98:101]
	v_mfma_f32_16x16x32_bf16 v[90:93], v[142:145], v[206:209], v[90:93]
	v_mfma_f32_16x16x32_bf16 v[82:85], v[134:137], v[214:217], v[82:85]
	v_mfma_f32_16x16x32_bf16 v[74:77], v[142:145], v[214:217], v[74:77]
	v_mfma_f32_16x16x32_bf16 v[118:121], v[146:149], v[162:165], 0
	v_mfma_f32_16x16x32_bf16 v[114:117], v[154:157], v[162:165], 0
	v_mfma_f32_16x16x32_bf16 v[102:105], v[146:149], v[184:187], 0
	v_mfma_f32_16x16x32_bf16 v[94:97], v[154:157], v[184:187], 0
	v_mfma_f32_16x16x32_bf16 v[86:89], v[146:149], v[202:205], 0
	v_mfma_f32_16x16x32_bf16 v[78:81], v[154:157], v[202:205], 0
	v_mfma_f32_16x16x32_bf16 v[70:73], v[146:149], v[210:213], 0
	v_mfma_f32_16x16x32_bf16 v[66:69], v[154:157], v[210:213], 0
	v_mfma_f32_16x16x32_bf16 v[118:121], v[150:153], v[180:183], v[118:121]
	v_mfma_f32_16x16x32_bf16 v[114:117], v[158:161], v[180:183], v[114:117]
	v_mfma_f32_16x16x32_bf16 v[102:105], v[150:153], v[190:193], v[102:105]
	v_mfma_f32_16x16x32_bf16 v[94:97], v[158:161], v[190:193], v[94:97]
	v_mfma_f32_16x16x32_bf16 v[86:89], v[150:153], v[206:209], v[86:89]
	v_mfma_f32_16x16x32_bf16 v[78:81], v[158:161], v[206:209], v[78:81]
	v_mfma_f32_16x16x32_bf16 v[70:73], v[150:153], v[214:217], v[70:73]
	v_mfma_f32_16x16x32_bf16 v[66:69], v[158:161], v[214:217], v[66:69]
	s_barrier
	s_setprio 0
	s_add_i32 s0, s78, s26
	s_add_u32 s98, s8, s16
	s_addc_u32 s99, s9, s17
	s_mov_b32 m0, s0
	ds_read_b128 v[162:165], v189 offset:16384
	ds_read_b128 v[180:183], v189 offset:17408
	ds_read_b128 v[184:187], v189 offset:18432
	ds_read_b128 v[190:193], v189 offset:19456
	ds_read_b128 v[202:205], v189 offset:20480
	ds_read_b128 v[206:209], v189 offset:21504
	ds_read_b128 v[210:213], v189 offset:22528
	ds_read_b128 v[214:217], v189 offset:23552
	global_load_lds_dwordx4 v196, s[8:9]
	s_add_i32 m0, s0, 0x2000
	s_add_u32 s0, s8, 0x80000
	s_addc_u32 s1, s9, 0
	s_add_i32 s78, s79, s26
	global_load_lds_dwordx4 v170, s[8:9]
	s_mov_b32 m0, s78
	v_lshl_add_u64 v[222:223], s[64:65], 0, v[168:169]
	global_load_lds_dwordx4 v196, s[0:1]
	s_add_i32 m0, s78, 0x2000
	s_nop 0
	global_load_lds_dwordx4 v170, s[0:1]
	v_lshl_add_u64 v[220:221], s[64:65], 0, v[166:167]
	s_mov_b32 m0, s27
	s_nop 0
	global_load_lds_dwordx4 v166, s[64:65]
	s_mov_b32 m0, s28
	s_nop 0
	global_load_lds_dwordx4 v168, s[64:65]
	s_waitcnt vmcnt(8)
	s_waitcnt lgkmcnt(0)
	s_setprio 1
	s_barrier
	v_mfma_f32_16x16x32_bf16 v[62:65], v[130:133], v[162:165], 0
	v_mfma_f32_16x16x32_bf16 v[58:61], v[138:141], v[162:165], 0
	v_mfma_f32_16x16x32_bf16 v[50:53], v[130:133], v[184:187], 0
	v_mfma_f32_16x16x32_bf16 v[42:45], v[138:141], v[184:187], 0
	v_mfma_f32_16x16x32_bf16 v[34:37], v[130:133], v[202:205], 0
	v_mfma_f32_16x16x32_bf16 v[26:29], v[138:141], v[202:205], 0
	v_mfma_f32_16x16x32_bf16 v[18:21], v[130:133], v[210:213], 0
	v_mfma_f32_16x16x32_bf16 v[10:13], v[138:141], v[210:213], 0
	v_mfma_f32_16x16x32_bf16 v[62:65], v[134:137], v[180:183], v[62:65]
	v_mfma_f32_16x16x32_bf16 v[58:61], v[142:145], v[180:183], v[58:61]
	v_mfma_f32_16x16x32_bf16 v[50:53], v[134:137], v[190:193], v[50:53]
	v_mfma_f32_16x16x32_bf16 v[42:45], v[142:145], v[190:193], v[42:45]
	v_mfma_f32_16x16x32_bf16 v[34:37], v[134:137], v[206:209], v[34:37]
	v_mfma_f32_16x16x32_bf16 v[26:29], v[142:145], v[206:209], v[26:29]
	v_mfma_f32_16x16x32_bf16 v[18:21], v[134:137], v[214:217], v[18:21]
	v_mfma_f32_16x16x32_bf16 v[10:13], v[142:145], v[214:217], v[10:13]
	v_mfma_f32_16x16x32_bf16 v[54:57], v[146:149], v[162:165], 0
	v_mfma_f32_16x16x32_bf16 v[46:49], v[154:157], v[162:165], 0
	v_mfma_f32_16x16x32_bf16 v[38:41], v[146:149], v[184:187], 0
	v_mfma_f32_16x16x32_bf16 v[30:33], v[154:157], v[184:187], 0
	v_mfma_f32_16x16x32_bf16 v[22:25], v[146:149], v[202:205], 0
	v_mfma_f32_16x16x32_bf16 v[14:17], v[154:157], v[202:205], 0
	v_mfma_f32_16x16x32_bf16 v[6:9], v[146:149], v[210:213], 0
	v_mfma_f32_16x16x32_bf16 v[2:5], v[154:157], v[210:213], 0
	v_mfma_f32_16x16x32_bf16 v[54:57], v[150:153], v[180:183], v[54:57]
	v_mfma_f32_16x16x32_bf16 v[46:49], v[158:161], v[180:183], v[46:49]
	v_mfma_f32_16x16x32_bf16 v[38:41], v[150:153], v[190:193], v[38:41]
	v_mfma_f32_16x16x32_bf16 v[30:33], v[158:161], v[190:193], v[30:33]
	v_mfma_f32_16x16x32_bf16 v[22:25], v[150:153], v[206:209], v[22:25]
	v_mfma_f32_16x16x32_bf16 v[14:17], v[158:161], v[206:209], v[14:17]
	v_mfma_f32_16x16x32_bf16 v[6:9], v[150:153], v[214:217], v[6:9]
	v_mfma_f32_16x16x32_bf16 v[2:5], v[158:161], v[214:217], v[2:5]
	s_barrier
	s_setprio 0
	s_branch .Lkmid_4

.Lkmid_4:
	s_add_i32 s78, 0, 0x18000
	s_add_i32 s79, 0, 0x1c000
	v_add_u32_e32 v142, s78, v188
	v_add_u32_e32 v158, s79, v188
	ds_read_b128 v[130:133], v142
	ds_read_b128 v[134:137], v142 offset:1024
	ds_read_b128 v[138:141], v142 offset:2048
	ds_read_b128 v[142:145], v142 offset:3072
	ds_read_b128 v[146:149], v158
	ds_read_b128 v[150:153], v158 offset:1024
	ds_read_b128 v[154:157], v158 offset:2048
	ds_read_b128 v[158:161], v158 offset:3072
	s_add_u32 s0, s64, 0x80000
	s_addc_u32 s1, s65, 0
	s_mov_b32 m0, s29
	ds_read_b128 v[162:165], v189 offset:32768
	ds_read_b128 v[180:183], v189 offset:33792
	ds_read_b128 v[184:187], v189 offset:34816
	ds_read_b128 v[190:193], v189 offset:35840
	ds_read_b128 v[202:205], v189 offset:36864
	ds_read_b128 v[206:209], v189 offset:37888
	ds_read_b128 v[210:213], v189 offset:38912
	ds_read_b128 v[214:217], v189 offset:39936
	global_load_lds_dwordx4 v166, s[0:1]
	s_mov_b32 m0, s30
	s_nop 0
	global_load_lds_dwordx4 v168, s[0:1]
	s_waitcnt vmcnt(8)
	s_waitcnt lgkmcnt(0)
	s_setprio 1
	s_barrier
	v_mfma_f32_16x16x32_bf16 v[126:129], v[130:133], v[162:165], v[126:129]
	v_mfma_f32_16x16x32_bf16 v[122:125], v[138:141], v[162:165], v[122:125]
	v_mfma_f32_16x16x32_bf16 v[110:113], v[130:133], v[184:187], v[110:113]
	v_mfma_f32_16x16x32_bf16 v[106:109], v[138:141], v[184:187], v[106:109]
	v_mfma_f32_16x16x32_bf16 v[98:101], v[130:133], v[202:205], v[98:101]
	v_mfma_f32_16x16x32_bf16 v[90:93], v[138:141], v[202:205], v[90:93]
	v_mfma_f32_16x16x32_bf16 v[82:85], v[130:133], v[210:213], v[82:85]
	v_mfma_f32_16x16x32_bf16 v[74:77], v[138:141], v[210:213], v[74:77]
	v_mfma_f32_16x16x32_bf16 v[126:129], v[134:137], v[180:183], v[126:129]
	v_mfma_f32_16x16x32_bf16 v[122:125], v[142:145], v[180:183], v[122:125]
	v_mfma_f32_16x16x32_bf16 v[110:113], v[134:137], v[190:193], v[110:113]
	v_mfma_f32_16x16x32_bf16 v[106:109], v[142:145], v[190:193], v[106:109]
	v_mfma_f32_16x16x32_bf16 v[98:101], v[134:137], v[206:209], v[98:101]
	v_mfma_f32_16x16x32_bf16 v[90:93], v[142:145], v[206:209], v[90:93]
	v_mfma_f32_16x16x32_bf16 v[82:85], v[134:137], v[214:217], v[82:85]
	v_mfma_f32_16x16x32_bf16 v[74:77], v[142:145], v[214:217], v[74:77]
	v_mfma_f32_16x16x32_bf16 v[118:121], v[146:149], v[162:165], v[118:121]
	v_mfma_f32_16x16x32_bf16 v[114:117], v[154:157], v[162:165], v[114:117]
	v_mfma_f32_16x16x32_bf16 v[102:105], v[146:149], v[184:187], v[102:105]
	v_mfma_f32_16x16x32_bf16 v[94:97], v[154:157], v[184:187], v[94:97]
	v_mfma_f32_16x16x32_bf16 v[86:89], v[146:149], v[202:205], v[86:89]
	v_mfma_f32_16x16x32_bf16 v[78:81], v[154:157], v[202:205], v[78:81]
	v_mfma_f32_16x16x32_bf16 v[70:73], v[146:149], v[210:213], v[70:73]
	v_mfma_f32_16x16x32_bf16 v[66:69], v[154:157], v[210:213], v[66:69]
	v_mfma_f32_16x16x32_bf16 v[118:121], v[150:153], v[180:183], v[118:121]
	v_mfma_f32_16x16x32_bf16 v[114:117], v[158:161], v[180:183], v[114:117]
	v_mfma_f32_16x16x32_bf16 v[102:105], v[150:153], v[190:193], v[102:105]
	v_mfma_f32_16x16x32_bf16 v[94:97], v[158:161], v[190:193], v[94:97]
	v_mfma_f32_16x16x32_bf16 v[86:89], v[150:153], v[206:209], v[86:89]
	v_mfma_f32_16x16x32_bf16 v[78:81], v[158:161], v[206:209], v[78:81]
	v_mfma_f32_16x16x32_bf16 v[70:73], v[150:153], v[214:217], v[70:73]
	v_mfma_f32_16x16x32_bf16 v[66:69], v[158:161], v[214:217], v[66:69]
	s_barrier
	s_setprio 0
	s_add_i32 s0, s78, s26
	s_mov_b32 m0, s0
	ds_read_b128 v[162:165], v189 offset:49152
	ds_read_b128 v[180:183], v189 offset:50176
	ds_read_b128 v[184:187], v189 offset:51200
	ds_read_b128 v[190:193], v189 offset:52224
	ds_read_b128 v[202:205], v189 offset:53248
	ds_read_b128 v[206:209], v189 offset:54272
	ds_read_b128 v[210:213], v189 offset:55296
	ds_read_b128 v[214:217], v189 offset:56320
	global_load_lds_dwordx4 v196, s[98:99]
	s_add_i32 m0, s0, 0x2000
	s_add_u32 s0, s8, 0x80080
	s_addc_u32 s1, s9, 0
	s_add_i32 s8, s79, s26
	global_load_lds_dwordx4 v170, s[98:99]
	s_mov_b32 m0, s8
	s_nop 0
	global_load_lds_dwordx4 v196, s[0:1]
	s_add_i32 m0, s8, 0x2000
	s_nop 0
	global_load_lds_dwordx4 v170, s[0:1]
	v_lshl_add_u64 v[194:195], v[220:221], 0, s[16:17]
	s_mov_b32 m0, s35
	s_nop 0
	global_load_lds_dwordx4 v[194:195], off
	v_lshl_add_u64 v[194:195], v[222:223], 0, s[16:17]
	s_mov_b32 m0, s53
	s_nop 0
	global_load_lds_dwordx4 v[194:195], off
	s_waitcnt vmcnt(8)
	s_waitcnt lgkmcnt(0)
	s_setprio 1
	s_barrier
	v_mfma_f32_16x16x32_bf16 v[62:65], v[130:133], v[162:165], v[62:65]
	v_mfma_f32_16x16x32_bf16 v[58:61], v[138:141], v[162:165], v[58:61]
	v_mfma_f32_16x16x32_bf16 v[50:53], v[130:133], v[184:187], v[50:53]
	v_mfma_f32_16x16x32_bf16 v[42:45], v[138:141], v[184:187], v[42:45]
	v_mfma_f32_16x16x32_bf16 v[34:37], v[130:133], v[202:205], v[34:37]
	v_mfma_f32_16x16x32_bf16 v[26:29], v[138:141], v[202:205], v[26:29]
	v_mfma_f32_16x16x32_bf16 v[18:21], v[130:133], v[210:213], v[18:21]
	v_mfma_f32_16x16x32_bf16 v[10:13], v[138:141], v[210:213], v[10:13]
	v_mfma_f32_16x16x32_bf16 v[62:65], v[134:137], v[180:183], v[62:65]
	v_mfma_f32_16x16x32_bf16 v[58:61], v[142:145], v[180:183], v[58:61]
	v_mfma_f32_16x16x32_bf16 v[50:53], v[134:137], v[190:193], v[50:53]
	v_mfma_f32_16x16x32_bf16 v[42:45], v[142:145], v[190:193], v[42:45]
	v_mfma_f32_16x16x32_bf16 v[34:37], v[134:137], v[206:209], v[34:37]
	v_mfma_f32_16x16x32_bf16 v[26:29], v[142:145], v[206:209], v[26:29]
	v_mfma_f32_16x16x32_bf16 v[18:21], v[134:137], v[214:217], v[18:21]
	v_mfma_f32_16x16x32_bf16 v[10:13], v[142:145], v[214:217], v[10:13]
	v_mfma_f32_16x16x32_bf16 v[54:57], v[146:149], v[162:165], v[54:57]
	v_mfma_f32_16x16x32_bf16 v[46:49], v[154:157], v[162:165], v[46:49]
	v_mfma_f32_16x16x32_bf16 v[38:41], v[146:149], v[184:187], v[38:41]
	v_mfma_f32_16x16x32_bf16 v[30:33], v[154:157], v[184:187], v[30:33]
	v_mfma_f32_16x16x32_bf16 v[22:25], v[146:149], v[202:205], v[22:25]
	v_mfma_f32_16x16x32_bf16 v[14:17], v[154:157], v[202:205], v[14:17]
	v_mfma_f32_16x16x32_bf16 v[6:9], v[146:149], v[210:213], v[6:9]
	v_mfma_f32_16x16x32_bf16 v[2:5], v[154:157], v[210:213], v[2:5]
	v_mfma_f32_16x16x32_bf16 v[54:57], v[150:153], v[180:183], v[54:57]
	v_mfma_f32_16x16x32_bf16 v[46:49], v[158:161], v[180:183], v[46:49]
	v_mfma_f32_16x16x32_bf16 v[38:41], v[150:153], v[190:193], v[38:41]
	v_mfma_f32_16x16x32_bf16 v[30:33], v[158:161], v[190:193], v[30:33]
	v_mfma_f32_16x16x32_bf16 v[22:25], v[150:153], v[206:209], v[22:25]
	v_mfma_f32_16x16x32_bf16 v[14:17], v[158:161], v[206:209], v[14:17]
	v_mfma_f32_16x16x32_bf16 v[6:9], v[150:153], v[214:217], v[6:9]
	v_mfma_f32_16x16x32_bf16 v[2:5], v[158:161], v[214:217], v[2:5]
	s_barrier
	s_setprio 0
	s_add_u32 s72, s72, 0x100
	s_addc_u32 s73, s73, 0
	s_add_u32 s62, s62, 0x100
	s_addc_u32 s63, s63, 0
	s_cmp_ge_i32 s77, s69
	s_mov_b32 s8, s77
	s_cbranch_scc0 .LBB0_2357
	s_and_b64 vcc, exec, s[38:39]
	s_cbranch_vccz .LBB0_2360
	s_barrier

.LBB0_2506:
	s_ashr_i32 s45, s44, 31
	s_lshl_b64 s[0:1], s[44:45], 20
	s_add_u32 s43, s2, s0
	s_addc_u32 s45, s3, s1
	s_ashr_i32 s41, s40, 31
	s_lshl_b64 s[0:1], s[40:41], 1
	s_add_u32 s48, s43, s0
	s_addc_u32 s49, s45, s1
	s_and_b64 s[50:51], s[46:47], exec
	s_cselect_b32 s41, s49, s9
	s_cselect_b32 s45, s48, s8
	s_ashr_i32 s43, s42, 31
	s_lshl_b64 s[50:51], s[42:43], 20
	s_add_u32 s43, s10, s50
	s_addc_u32 s51, s11, s51
	s_add_u32 s50, s43, s0
	s_addc_u32 s51, s51, s1
	s_and_b64 s[0:1], s[46:47], exec
	s_cselect_b32 s43, s51, s53
	s_cselect_b32 s65, s50, s52
	s_add_i32 s66, s62, -2
	s_add_u32 s67, s52, 0x100
	s_addc_u32 s68, s53, 0
	s_add_u32 s52, s8, 0x80080
	s_addc_u32 s53, s9, 0
	s_mov_b32 s8, 0
	s_cmp_eq_u32 s100, 1
	s_cbranch_scc0 .Ldefbar_skip_5
	s_mov_b32 s100, 0
	s_barrier
.Ldefbar_skip_5:
	s_add_i32 s69, s8, 2
	s_add_u32 s0, s52, 0xfff80080
	s_addc_u32 s1, s53, -1
	s_add_i32 s70, 0, 0x10000
	s_cmp_eq_u32 s66, s8
	s_cselect_b32 s59, s41, s1
	s_cselect_b32 s58, s45, s0
	s_cselect_b32 s9, s43, s68
	s_cselect_b32 s8, s65, s67
	s_add_i32 s71, 0, 0x14000
	v_add_u32_e32 v156, s70, v141
	v_add_u32_e32 v172, s71, v141
	ds_read_b128 v[144:147], v156
	ds_read_b128 v[148:151], v156 offset:1024
	ds_read_b128 v[152:155], v156 offset:2048
	ds_read_b128 v[156:159], v156 offset:3072
	ds_read_b128 v[160:163], v172
	ds_read_b128 v[164:167], v172 offset:1024
	ds_read_b128 v[168:171], v172 offset:2048
	ds_read_b128 v[172:175], v172 offset:3072
	s_add_i32 m0, s27, 0xc000
	ds_read_b128 v[176:179], v143
	ds_read_b128 v[180:183], v143 offset:1024
	ds_read_b128 v[184:187], v143 offset:2048
	ds_read_b128 v[188:191], v143 offset:3072
	ds_read_b128 v[192:195], v143 offset:4096
	ds_read_b128 v[202:205], v143 offset:5120
	ds_read_b128 v[206:209], v143 offset:6144
	ds_read_b128 v[210:213], v143 offset:7168
	global_load_lds_dwordx4 v138, s[52:53]
	s_add_i32 m0, s27, 0xe000
	s_nop 0
	global_load_lds_dwordx4 v136, s[52:53]
	s_waitcnt vmcnt(8)
	s_waitcnt lgkmcnt(0)
	s_setprio 1
	s_barrier
	v_mfma_f32_16x16x32_bf16 v[126:129], v[144:147], v[176:179], 0
	v_mfma_f32_16x16x32_bf16 v[118:121], v[152:155], v[176:179], 0
	v_mfma_f32_16x16x32_bf16 v[110:113], v[144:147], v[184:187], 0
	v_mfma_f32_16x16x32_bf16 v[102:105], v[152:155], v[184:187], 0
	v_mfma_f32_16x16x32_bf16 v[94:97], v[144:147], v[192:195], 0
	v_mfma_f32_16x16x32_bf16 v[86:89], v[152:155], v[192:195], 0
	v_mfma_f32_16x16x32_bf16 v[78:81], v[144:147], v[206:209], 0
	v_mfma_f32_16x16x32_bf16 v[70:73], v[152:155], v[206:209], 0
	v_mfma_f32_16x16x32_bf16 v[126:129], v[148:151], v[180:183], v[126:129]
	v_mfma_f32_16x16x32_bf16 v[118:121], v[156:159], v[180:183], v[118:121]
	v_mfma_f32_16x16x32_bf16 v[110:113], v[148:151], v[188:191], v[110:113]
	v_mfma_f32_16x16x32_bf16 v[102:105], v[156:159], v[188:191], v[102:105]
	v_mfma_f32_16x16x32_bf16 v[94:97], v[148:151], v[202:205], v[94:97]
	v_mfma_f32_16x16x32_bf16 v[86:89], v[156:159], v[202:205], v[86:89]
	v_mfma_f32_16x16x32_bf16 v[78:81], v[148:151], v[210:213], v[78:81]
	v_mfma_f32_16x16x32_bf16 v[70:73], v[156:159], v[210:213], v[70:73]
	v_mfma_f32_16x16x32_bf16 v[122:125], v[160:163], v[176:179], 0
	v_mfma_f32_16x16x32_bf16 v[114:117], v[168:171], v[176:179], 0
	v_mfma_f32_16x16x32_bf16 v[106:109], v[160:163], v[184:187], 0
	v_mfma_f32_16x16x32_bf16 v[98:101], v[168:171], v[184:187], 0
	v_mfma_f32_16x16x32_bf16 v[90:93], v[160:163], v[192:195], 0
	v_mfma_f32_16x16x32_bf16 v[82:85], v[168:171], v[192:195], 0
	v_mfma_f32_16x16x32_bf16 v[74:77], v[160:163], v[206:209], 0
	v_mfma_f32_16x16x32_bf16 v[66:69], v[168:171], v[206:209], 0
	v_mfma_f32_16x16x32_bf16 v[122:125], v[164:167], v[180:183], v[122:125]
	v_mfma_f32_16x16x32_bf16 v[114:117], v[172:175], v[180:183], v[114:117]
	v_mfma_f32_16x16x32_bf16 v[106:109], v[164:167], v[188:191], v[106:109]
	v_mfma_f32_16x16x32_bf16 v[98:101], v[172:175], v[188:191], v[98:101]
	v_mfma_f32_16x16x32_bf16 v[90:93], v[164:167], v[202:205], v[90:93]
	v_mfma_f32_16x16x32_bf16 v[82:85], v[172:175], v[202:205], v[82:85]
	v_mfma_f32_16x16x32_bf16 v[74:77], v[164:167], v[210:213], v[74:77]
	v_mfma_f32_16x16x32_bf16 v[66:69], v[172:175], v[210:213], v[66:69]
	s_barrier
	s_setprio 0
	s_add_i32 s0, s70, s26
	s_add_u32 s98, s8, s16
	s_addc_u32 s99, s9, s17
	s_mov_b32 m0, s0
	ds_read_b128 v[176:179], v143 offset:16384
	ds_read_b128 v[180:183], v143 offset:17408
	ds_read_b128 v[184:187], v143 offset:18432
	ds_read_b128 v[188:191], v143 offset:19456
	ds_read_b128 v[192:195], v143 offset:20480
	ds_read_b128 v[202:205], v143 offset:21504
	ds_read_b128 v[206:209], v143 offset:22528
	ds_read_b128 v[210:213], v143 offset:23552
	global_load_lds_dwordx4 v196, s[8:9]
	s_add_i32 m0, s0, 0x2000
	s_add_u32 s0, s8, 0x80000
	s_addc_u32 s1, s9, 0
	s_add_i32 s70, s71, s26
	global_load_lds_dwordx4 v130, s[8:9]
	s_mov_b32 m0, s70
	s_nop 0
	global_load_lds_dwordx4 v196, s[0:1]
	s_add_i32 m0, s70, 0x2000
	s_nop 0
	global_load_lds_dwordx4 v130, s[0:1]
	s_add_u32 s78, s58, s16
	s_addc_u32 s79, s59, s17
	s_mov_b32 m0, s27
	s_nop 0
	global_load_lds_dwordx4 v134, s[58:59]
	s_mov_b32 m0, s28
	s_nop 0
	global_load_lds_dwordx4 v132, s[58:59]
	s_waitcnt vmcnt(8)
	s_waitcnt lgkmcnt(0)
	s_setprio 1
	s_barrier
	v_mfma_f32_16x16x32_bf16 v[62:65], v[144:147], v[176:179], 0
	v_mfma_f32_16x16x32_bf16 v[54:57], v[152:155], v[176:179], 0
	v_mfma_f32_16x16x32_bf16 v[46:49], v[144:147], v[184:187], 0
	v_mfma_f32_16x16x32_bf16 v[38:41], v[152:155], v[184:187], 0
	v_mfma_f32_16x16x32_bf16 v[30:33], v[144:147], v[192:195], 0
	v_mfma_f32_16x16x32_bf16 v[22:25], v[152:155], v[192:195], 0
	v_mfma_f32_16x16x32_bf16 v[14:17], v[144:147], v[206:209], 0
	v_mfma_f32_16x16x32_bf16 v[6:9], v[152:155], v[206:209], 0
	v_mfma_f32_16x16x32_bf16 v[62:65], v[148:151], v[180:183], v[62:65]
	v_mfma_f32_16x16x32_bf16 v[54:57], v[156:159], v[180:183], v[54:57]
	v_mfma_f32_16x16x32_bf16 v[46:49], v[148:151], v[188:191], v[46:49]
	v_mfma_f32_16x16x32_bf16 v[38:41], v[156:159], v[188:191], v[38:41]
	v_mfma_f32_16x16x32_bf16 v[30:33], v[148:151], v[202:205], v[30:33]
	v_mfma_f32_16x16x32_bf16 v[22:25], v[156:159], v[202:205], v[22:25]
	v_mfma_f32_16x16x32_bf16 v[14:17], v[148:151], v[210:213], v[14:17]
	v_mfma_f32_16x16x32_bf16 v[6:9], v[156:159], v[210:213], v[6:9]
	v_mfma_f32_16x16x32_bf16 v[58:61], v[160:163], v[176:179], 0
	v_mfma_f32_16x16x32_bf16 v[50:53], v[168:171], v[176:179], 0
	v_mfma_f32_16x16x32_bf16 v[42:45], v[160:163], v[184:187], 0
	v_mfma_f32_16x16x32_bf16 v[34:37], v[168:171], v[184:187], 0
	v_mfma_f32_16x16x32_bf16 v[26:29], v[160:163], v[192:195], 0
	v_mfma_f32_16x16x32_bf16 v[18:21], v[168:171], v[192:195], 0
	v_mfma_f32_16x16x32_bf16 v[10:13], v[160:163], v[206:209], 0
	v_mfma_f32_16x16x32_bf16 v[2:5], v[168:171], v[206:209], 0
	v_mfma_f32_16x16x32_bf16 v[58:61], v[164:167], v[180:183], v[58:61]
	v_mfma_f32_16x16x32_bf16 v[50:53], v[172:175], v[180:183], v[50:53]
	v_mfma_f32_16x16x32_bf16 v[42:45], v[164:167], v[188:191], v[42:45]
	v_mfma_f32_16x16x32_bf16 v[34:37], v[172:175], v[188:191], v[34:37]
	v_mfma_f32_16x16x32_bf16 v[26:29], v[164:167], v[202:205], v[26:29]
	v_mfma_f32_16x16x32_bf16 v[18:21], v[172:175], v[202:205], v[18:21]
	v_mfma_f32_16x16x32_bf16 v[10:13], v[164:167], v[210:213], v[10:13]
	v_mfma_f32_16x16x32_bf16 v[2:5], v[172:175], v[210:213], v[2:5]
	s_barrier
	s_setprio 0
	s_branch .Lkmid_5

.Lkmid_5:
	s_add_i32 s70, 0, 0x18000
	s_add_i32 s71, 0, 0x1c000
	v_add_u32_e32 v156, s70, v141
	v_add_u32_e32 v172, s71, v141
	ds_read_b128 v[144:147], v156
	ds_read_b128 v[148:151], v156 offset:1024
	ds_read_b128 v[152:155], v156 offset:2048
	ds_read_b128 v[156:159], v156 offset:3072
	ds_read_b128 v[160:163], v172
	ds_read_b128 v[164:167], v172 offset:1024
	ds_read_b128 v[168:171], v172 offset:2048
	ds_read_b128 v[172:175], v172 offset:3072
	s_add_u32 s0, s58, 0x80000
	s_addc_u32 s1, s59, 0
	s_mov_b32 m0, s29
	ds_read_b128 v[176:179], v143 offset:32768
	ds_read_b128 v[180:183], v143 offset:33792
	ds_read_b128 v[184:187], v143 offset:34816
	ds_read_b128 v[188:191], v143 offset:35840
	ds_read_b128 v[192:195], v143 offset:36864
	ds_read_b128 v[202:205], v143 offset:37888
	ds_read_b128 v[206:209], v143 offset:38912
	ds_read_b128 v[210:213], v143 offset:39936
	global_load_lds_dwordx4 v134, s[0:1]
	s_mov_b32 m0, s30
	s_nop 0
	global_load_lds_dwordx4 v132, s[0:1]
	s_waitcnt vmcnt(8)
	s_waitcnt lgkmcnt(0)
	s_setprio 1
	s_barrier
	v_mfma_f32_16x16x32_bf16 v[126:129], v[144:147], v[176:179], v[126:129]
	v_mfma_f32_16x16x32_bf16 v[118:121], v[152:155], v[176:179], v[118:121]
	v_mfma_f32_16x16x32_bf16 v[110:113], v[144:147], v[184:187], v[110:113]
	v_mfma_f32_16x16x32_bf16 v[102:105], v[152:155], v[184:187], v[102:105]
	v_mfma_f32_16x16x32_bf16 v[94:97], v[144:147], v[192:195], v[94:97]
	v_mfma_f32_16x16x32_bf16 v[86:89], v[152:155], v[192:195], v[86:89]
	v_mfma_f32_16x16x32_bf16 v[78:81], v[144:147], v[206:209], v[78:81]
	v_mfma_f32_16x16x32_bf16 v[70:73], v[152:155], v[206:209], v[70:73]
	v_mfma_f32_16x16x32_bf16 v[126:129], v[148:151], v[180:183], v[126:129]
	v_mfma_f32_16x16x32_bf16 v[118:121], v[156:159], v[180:183], v[118:121]
	v_mfma_f32_16x16x32_bf16 v[110:113], v[148:151], v[188:191], v[110:113]
	v_mfma_f32_16x16x32_bf16 v[102:105], v[156:159], v[188:191], v[102:105]
	v_mfma_f32_16x16x32_bf16 v[94:97], v[148:151], v[202:205], v[94:97]
	v_mfma_f32_16x16x32_bf16 v[86:89], v[156:159], v[202:205], v[86:89]
	v_mfma_f32_16x16x32_bf16 v[78:81], v[148:151], v[210:213], v[78:81]
	v_mfma_f32_16x16x32_bf16 v[70:73], v[156:159], v[210:213], v[70:73]
	v_mfma_f32_16x16x32_bf16 v[122:125], v[160:163], v[176:179], v[122:125]
	v_mfma_f32_16x16x32_bf16 v[114:117], v[168:171], v[176:179], v[114:117]
	v_mfma_f32_16x16x32_bf16 v[106:109], v[160:163], v[184:187], v[106:109]
	v_mfma_f32_16x16x32_bf16 v[98:101], v[168:171], v[184:187], v[98:101]
	v_mfma_f32_16x16x32_bf16 v[90:93], v[160:163], v[192:195], v[90:93]
	v_mfma_f32_16x16x32_bf16 v[82:85], v[168:171], v[192:195], v[82:85]
	v_mfma_f32_16x16x32_bf16 v[74:77], v[160:163], v[206:209], v[74:77]
	v_mfma_f32_16x16x32_bf16 v[66:69], v[168:171], v[206:209], v[66:69]
	v_mfma_f32_16x16x32_bf16 v[122:125], v[164:167], v[180:183], v[122:125]
	v_mfma_f32_16x16x32_bf16 v[114:117], v[172:175], v[180:183], v[114:117]
	v_mfma_f32_16x16x32_bf16 v[106:109], v[164:167], v[188:191], v[106:109]
	v_mfma_f32_16x16x32_bf16 v[98:101], v[172:175], v[188:191], v[98:101]
	v_mfma_f32_16x16x32_bf16 v[90:93], v[164:167], v[202:205], v[90:93]
	v_mfma_f32_16x16x32_bf16 v[82:85], v[172:175], v[202:205], v[82:85]
	v_mfma_f32_16x16x32_bf16 v[74:77], v[164:167], v[210:213], v[74:77]
	v_mfma_f32_16x16x32_bf16 v[66:69], v[172:175], v[210:213], v[66:69]
	s_barrier
	s_setprio 0
	s_add_i32 s0, s70, s26
	s_mov_b32 m0, s0
	ds_read_b128 v[176:179], v143 offset:49152
	ds_read_b128 v[180:183], v143 offset:50176
	ds_read_b128 v[184:187], v143 offset:51200
	ds_read_b128 v[188:191], v143 offset:52224
	ds_read_b128 v[192:195], v143 offset:53248
	ds_read_b128 v[202:205], v143 offset:54272
	ds_read_b128 v[206:209], v143 offset:55296
	ds_read_b128 v[210:213], v143 offset:56320
	global_load_lds_dwordx4 v196, s[98:99]
	s_add_i32 m0, s0, 0x2000
	s_add_u32 s0, s8, 0x80080
	s_addc_u32 s1, s9, 0
	s_add_i32 s8, s71, s26
	global_load_lds_dwordx4 v130, s[98:99]
	s_mov_b32 m0, s8
	s_nop 0
	global_load_lds_dwordx4 v196, s[0:1]
	s_add_i32 m0, s8, 0x2000
	s_nop 0
	global_load_lds_dwordx4 v130, s[0:1]
	s_mov_b32 m0, s31
	s_nop 0
	global_load_lds_dwordx4 v134, s[78:79]
	s_mov_b32 m0, s34
	s_nop 0
	global_load_lds_dwordx4 v132, s[78:79]
	s_waitcnt vmcnt(8)
	s_waitcnt lgkmcnt(0)
	s_setprio 1
	s_barrier
	v_mfma_f32_16x16x32_bf16 v[62:65], v[144:147], v[176:179], v[62:65]
	v_mfma_f32_16x16x32_bf16 v[54:57], v[152:155], v[176:179], v[54:57]
	v_mfma_f32_16x16x32_bf16 v[46:49], v[144:147], v[184:187], v[46:49]
	v_mfma_f32_16x16x32_bf16 v[38:41], v[152:155], v[184:187], v[38:41]
	v_mfma_f32_16x16x32_bf16 v[30:33], v[144:147], v[192:195], v[30:33]
	v_mfma_f32_16x16x32_bf16 v[22:25], v[152:155], v[192:195], v[22:25]
	v_mfma_f32_16x16x32_bf16 v[14:17], v[144:147], v[206:209], v[14:17]
	v_mfma_f32_16x16x32_bf16 v[6:9], v[152:155], v[206:209], v[6:9]
	v_mfma_f32_16x16x32_bf16 v[62:65], v[148:151], v[180:183], v[62:65]
	v_mfma_f32_16x16x32_bf16 v[54:57], v[156:159], v[180:183], v[54:57]
	v_mfma_f32_16x16x32_bf16 v[46:49], v[148:151], v[188:191], v[46:49]
	v_mfma_f32_16x16x32_bf16 v[38:41], v[156:159], v[188:191], v[38:41]
	v_mfma_f32_16x16x32_bf16 v[30:33], v[148:151], v[202:205], v[30:33]
	v_mfma_f32_16x16x32_bf16 v[22:25], v[156:159], v[202:205], v[22:25]
	v_mfma_f32_16x16x32_bf16 v[14:17], v[148:151], v[210:213], v[14:17]
	v_mfma_f32_16x16x32_bf16 v[6:9], v[156:159], v[210:213], v[6:9]
	v_mfma_f32_16x16x32_bf16 v[58:61], v[160:163], v[176:179], v[58:61]
	v_mfma_f32_16x16x32_bf16 v[50:53], v[168:171], v[176:179], v[50:53]
	v_mfma_f32_16x16x32_bf16 v[42:45], v[160:163], v[184:187], v[42:45]
	v_mfma_f32_16x16x32_bf16 v[34:37], v[168:171], v[184:187], v[34:37]
	v_mfma_f32_16x16x32_bf16 v[26:29], v[160:163], v[192:195], v[26:29]
	v_mfma_f32_16x16x32_bf16 v[18:21], v[168:171], v[192:195], v[18:21]
	v_mfma_f32_16x16x32_bf16 v[10:13], v[160:163], v[206:209], v[10:13]
	v_mfma_f32_16x16x32_bf16 v[2:5], v[168:171], v[206:209], v[2:5]
	v_mfma_f32_16x16x32_bf16 v[58:61], v[164:167], v[180:183], v[58:61]
	v_mfma_f32_16x16x32_bf16 v[50:53], v[172:175], v[180:183], v[50:53]
	v_mfma_f32_16x16x32_bf16 v[42:45], v[164:167], v[188:191], v[42:45]
	v_mfma_f32_16x16x32_bf16 v[34:37], v[172:175], v[188:191], v[34:37]
	v_mfma_f32_16x16x32_bf16 v[26:29], v[164:167], v[202:205], v[26:29]
	v_mfma_f32_16x16x32_bf16 v[18:21], v[172:175], v[202:205], v[18:21]
	v_mfma_f32_16x16x32_bf16 v[10:13], v[164:167], v[210:213], v[10:13]
	v_mfma_f32_16x16x32_bf16 v[2:5], v[172:175], v[210:213], v[2:5]
	s_barrier
	s_setprio 0
	s_add_u32 s67, s67, 0x100
	s_addc_u32 s68, s68, 0
	s_add_u32 s52, s52, 0x100
	s_addc_u32 s53, s53, 0
	s_cmp_ge_i32 s69, s62
	s_mov_b32 s8, s69
	s_cbranch_scc0 .LBB0_2507
	s_and_b64 vcc, exec, s[38:39]
	s_cbranch_vccz .LBB0_2510
	s_barrier

.LBB0_2587:
	s_add_i32 s41, s69, -2
	s_add_u32 s70, s8, 0x100
	s_addc_u32 s71, s9, 0
	s_mov_b32 s48, 0
	s_nop 0
	s_cmp_eq_u32 s100, 1
	s_cbranch_scc0 .Ldefbar_skip_6
	s_mov_b32 s100, 0
	s_barrier
.Ldefbar_skip_6:
	s_add_i32 s72, s48, 2
	s_add_u32 s8, s46, 0x100
	s_addc_u32 s9, s47, 0
	s_add_i32 s0, 0, 0x10000
	s_cmp_eq_u32 s41, s48
	s_cselect_b32 s51, s43, s9
	s_cselect_b32 s50, s42, s8
	s_cselect_b32 s49, s45, s71
	s_cselect_b32 s48, s44, s70
	s_add_i32 s73, 0, 0x14000
	v_add_u32_e32 v142, s0, v188
	v_add_u32_e32 v172, s73, v188
	ds_read_b128 v[130:133], v142
	ds_read_b128 v[134:137], v142 offset:1024
	ds_read_b128 v[138:141], v142 offset:2048
	ds_read_b128 v[142:145], v142 offset:3072
	ds_read_b128 v[146:149], v172
	ds_read_b128 v[164:167], v172 offset:1024
	ds_read_b128 v[168:171], v172 offset:2048
	ds_read_b128 v[172:175], v172 offset:3072
	v_lshl_add_u64 v[194:195], s[46:47], 0, v[162:163]
	s_add_i32 m0, s27, 0xc000
	ds_read_b128 v[176:179], v189
	ds_read_b128 v[180:183], v189 offset:1024
	ds_read_b128 v[184:187], v189 offset:2048
	ds_read_b128 v[190:193], v189 offset:3072
	ds_read_b128 v[202:205], v189 offset:4096
	ds_read_b128 v[206:209], v189 offset:5120
	ds_read_b128 v[210:213], v189 offset:6144
	ds_read_b128 v[214:217], v189 offset:7168
	global_load_lds_dwordx4 v[194:195], off
	v_lshl_add_u64 v[194:195], s[46:47], 0, v[160:161]
	s_add_i32 m0, s27, 0xe000
	s_nop 0
	global_load_lds_dwordx4 v[194:195], off
	s_waitcnt vmcnt(8)
	s_waitcnt lgkmcnt(0)
	s_setprio 1
	s_barrier
	v_mfma_f32_16x16x32_bf16 v[126:129], v[130:133], v[176:179], 0
	v_mfma_f32_16x16x32_bf16 v[122:125], v[138:141], v[176:179], 0
	v_mfma_f32_16x16x32_bf16 v[110:113], v[130:133], v[184:187], 0
	v_mfma_f32_16x16x32_bf16 v[106:109], v[138:141], v[184:187], 0
	v_mfma_f32_16x16x32_bf16 v[98:101], v[130:133], v[202:205], 0
	v_mfma_f32_16x16x32_bf16 v[90:93], v[138:141], v[202:205], 0
	v_mfma_f32_16x16x32_bf16 v[82:85], v[130:133], v[210:213], 0
	v_mfma_f32_16x16x32_bf16 v[74:77], v[138:141], v[210:213], 0
	v_mfma_f32_16x16x32_bf16 v[126:129], v[134:137], v[180:183], v[126:129]
	v_mfma_f32_16x16x32_bf16 v[122:125], v[142:145], v[180:183], v[122:125]
	v_mfma_f32_16x16x32_bf16 v[110:113], v[134:137], v[190:193], v[110:113]
	v_mfma_f32_16x16x32_bf16 v[106:109], v[142:145], v[190:193], v[106:109]
	v_mfma_f32_16x16x32_bf16 v[98:101], v[134:137], v[206:209], v[98:101]
	v_mfma_f32_16x16x32_bf16 v[90:93], v[142:145], v[206:209], v[90:93]
	v_mfma_f32_16x16x32_bf16 v[82:85], v[134:137], v[214:217], v[82:85]
	v_mfma_f32_16x16x32_bf16 v[74:77], v[142:145], v[214:217], v[74:77]
	v_mfma_f32_16x16x32_bf16 v[118:121], v[146:149], v[176:179], 0
	v_mfma_f32_16x16x32_bf16 v[114:117], v[168:171], v[176:179], 0
	v_mfma_f32_16x16x32_bf16 v[102:105], v[146:149], v[184:187], 0
	v_mfma_f32_16x16x32_bf16 v[94:97], v[168:171], v[184:187], 0
	v_mfma_f32_16x16x32_bf16 v[86:89], v[146:149], v[202:205], 0
	v_mfma_f32_16x16x32_bf16 v[78:81], v[168:171], v[202:205], 0
	v_mfma_f32_16x16x32_bf16 v[70:73], v[146:149], v[210:213], 0
	v_mfma_f32_16x16x32_bf16 v[66:69], v[168:171], v[210:213], 0
	v_mfma_f32_16x16x32_bf16 v[118:121], v[164:167], v[180:183], v[118:121]
	v_mfma_f32_16x16x32_bf16 v[114:117], v[172:175], v[180:183], v[114:117]
	v_mfma_f32_16x16x32_bf16 v[102:105], v[164:167], v[190:193], v[102:105]
	v_mfma_f32_16x16x32_bf16 v[94:97], v[172:175], v[190:193], v[94:97]
	v_mfma_f32_16x16x32_bf16 v[86:89], v[164:167], v[206:209], v[86:89]
	v_mfma_f32_16x16x32_bf16 v[78:81], v[172:175], v[206:209], v[78:81]
	v_mfma_f32_16x16x32_bf16 v[70:73], v[164:167], v[214:217], v[70:73]
	v_mfma_f32_16x16x32_bf16 v[66:69], v[172:175], v[214:217], v[66:69]
	s_barrier
	s_setprio 0
	s_add_i32 s0, s0, s26
	s_add_u32 s98, s48, s16
	s_addc_u32 s99, s49, s17
	s_mov_b32 m0, s0
	ds_read_b128 v[176:179], v189 offset:16384
	ds_read_b128 v[180:183], v189 offset:17408
	ds_read_b128 v[184:187], v189 offset:18432
	ds_read_b128 v[190:193], v189 offset:19456
	ds_read_b128 v[202:205], v189 offset:20480
	ds_read_b128 v[206:209], v189 offset:21504
	ds_read_b128 v[210:213], v189 offset:22528
	ds_read_b128 v[214:217], v189 offset:23552
	global_load_lds_dwordx4 v196, s[48:49]
	s_add_i32 m0, s0, 0x2000
	s_add_u32 s0, s48, 0x158000
	s_addc_u32 s1, s49, 0
	s_add_i32 s46, s73, s26
	global_load_lds_dwordx4 v154, s[48:49]
	s_mov_b32 m0, s46
	s_nop 0
	global_load_lds_dwordx4 v196, s[0:1]
	s_add_i32 m0, s46, 0x2000
	s_nop 0
	global_load_lds_dwordx4 v154, s[0:1]
	s_add_u32 s78, s50, s16
	s_addc_u32 s79, s51, s17
	s_mov_b32 m0, s27
	s_nop 0
	global_load_lds_dwordx4 v150, s[50:51]
	s_mov_b32 m0, s30
	s_nop 0
	global_load_lds_dwordx4 v152, s[50:51]
	s_waitcnt vmcnt(8)
	s_waitcnt lgkmcnt(0)
	s_setprio 1
	s_barrier
	v_mfma_f32_16x16x32_bf16 v[62:65], v[130:133], v[176:179], 0
	v_mfma_f32_16x16x32_bf16 v[58:61], v[138:141], v[176:179], 0
	v_mfma_f32_16x16x32_bf16 v[50:53], v[130:133], v[184:187], 0
	v_mfma_f32_16x16x32_bf16 v[42:45], v[138:141], v[184:187], 0
	v_mfma_f32_16x16x32_bf16 v[34:37], v[130:133], v[202:205], 0
	v_mfma_f32_16x16x32_bf16 v[26:29], v[138:141], v[202:205], 0
	v_mfma_f32_16x16x32_bf16 v[18:21], v[130:133], v[210:213], 0
	v_mfma_f32_16x16x32_bf16 v[10:13], v[138:141], v[210:213], 0
	v_mfma_f32_16x16x32_bf16 v[62:65], v[134:137], v[180:183], v[62:65]
	v_mfma_f32_16x16x32_bf16 v[58:61], v[142:145], v[180:183], v[58:61]
	v_mfma_f32_16x16x32_bf16 v[50:53], v[134:137], v[190:193], v[50:53]
	v_mfma_f32_16x16x32_bf16 v[42:45], v[142:145], v[190:193], v[42:45]
	v_mfma_f32_16x16x32_bf16 v[34:37], v[134:137], v[206:209], v[34:37]
	v_mfma_f32_16x16x32_bf16 v[26:29], v[142:145], v[206:209], v[26:29]
	v_mfma_f32_16x16x32_bf16 v[18:21], v[134:137], v[214:217], v[18:21]
	v_mfma_f32_16x16x32_bf16 v[10:13], v[142:145], v[214:217], v[10:13]
	v_mfma_f32_16x16x32_bf16 v[54:57], v[146:149], v[176:179], 0
	v_mfma_f32_16x16x32_bf16 v[46:49], v[168:171], v[176:179], 0
	v_mfma_f32_16x16x32_bf16 v[38:41], v[146:149], v[184:187], 0
	v_mfma_f32_16x16x32_bf16 v[30:33], v[168:171], v[184:187], 0
	v_mfma_f32_16x16x32_bf16 v[22:25], v[146:149], v[202:205], 0
	v_mfma_f32_16x16x32_bf16 v[14:17], v[168:171], v[202:205], 0
	v_mfma_f32_16x16x32_bf16 v[6:9], v[146:149], v[210:213], 0
	v_mfma_f32_16x16x32_bf16 v[2:5], v[168:171], v[210:213], 0
	v_mfma_f32_16x16x32_bf16 v[54:57], v[164:167], v[180:183], v[54:57]
	v_mfma_f32_16x16x32_bf16 v[46:49], v[172:175], v[180:183], v[46:49]
	v_mfma_f32_16x16x32_bf16 v[38:41], v[164:167], v[190:193], v[38:41]
	v_mfma_f32_16x16x32_bf16 v[30:33], v[172:175], v[190:193], v[30:33]
	v_mfma_f32_16x16x32_bf16 v[22:25], v[164:167], v[206:209], v[22:25]
	v_mfma_f32_16x16x32_bf16 v[14:17], v[172:175], v[206:209], v[14:17]
	v_mfma_f32_16x16x32_bf16 v[6:9], v[164:167], v[214:217], v[6:9]
	v_mfma_f32_16x16x32_bf16 v[2:5], v[172:175], v[214:217], v[2:5]
	s_barrier
	s_setprio 0
	s_branch .Lkmid_6

.Lkmid_6:
	s_add_i32 s46, 0, 0x18000
	s_add_i32 s47, 0, 0x1c000
	v_add_u32_e32 v142, s46, v188
	v_add_u32_e32 v172, s47, v188
	ds_read_b128 v[130:133], v142
	ds_read_b128 v[134:137], v142 offset:1024
	ds_read_b128 v[138:141], v142 offset:2048
	ds_read_b128 v[142:145], v142 offset:3072
	ds_read_b128 v[146:149], v172
	ds_read_b128 v[164:167], v172 offset:1024
	ds_read_b128 v[168:171], v172 offset:2048
	ds_read_b128 v[172:175], v172 offset:3072
	s_add_u32 s0, s50, 0x158000
	s_addc_u32 s1, s51, 0
	s_mov_b32 m0, s31
	ds_read_b128 v[176:179], v189 offset:32768
	ds_read_b128 v[180:183], v189 offset:33792
	ds_read_b128 v[184:187], v189 offset:34816
	ds_read_b128 v[190:193], v189 offset:35840
	ds_read_b128 v[202:205], v189 offset:36864
	ds_read_b128 v[206:209], v189 offset:37888
	ds_read_b128 v[210:213], v189 offset:38912
	ds_read_b128 v[214:217], v189 offset:39936
	global_load_lds_dwordx4 v150, s[0:1]
	s_mov_b32 m0, s34
	s_nop 0
	global_load_lds_dwordx4 v152, s[0:1]
	s_waitcnt vmcnt(8)
	s_waitcnt lgkmcnt(0)
	s_setprio 1
	s_barrier
	v_mfma_f32_16x16x32_bf16 v[126:129], v[130:133], v[176:179], v[126:129]
	v_mfma_f32_16x16x32_bf16 v[122:125], v[138:141], v[176:179], v[122:125]
	v_mfma_f32_16x16x32_bf16 v[110:113], v[130:133], v[184:187], v[110:113]
	v_mfma_f32_16x16x32_bf16 v[106:109], v[138:141], v[184:187], v[106:109]
	v_mfma_f32_16x16x32_bf16 v[98:101], v[130:133], v[202:205], v[98:101]
	v_mfma_f32_16x16x32_bf16 v[90:93], v[138:141], v[202:205], v[90:93]
	v_mfma_f32_16x16x32_bf16 v[82:85], v[130:133], v[210:213], v[82:85]
	v_mfma_f32_16x16x32_bf16 v[74:77], v[138:141], v[210:213], v[74:77]
	v_mfma_f32_16x16x32_bf16 v[126:129], v[134:137], v[180:183], v[126:129]
	v_mfma_f32_16x16x32_bf16 v[122:125], v[142:145], v[180:183], v[122:125]
	v_mfma_f32_16x16x32_bf16 v[110:113], v[134:137], v[190:193], v[110:113]
	v_mfma_f32_16x16x32_bf16 v[106:109], v[142:145], v[190:193], v[106:109]
	v_mfma_f32_16x16x32_bf16 v[98:101], v[134:137], v[206:209], v[98:101]
	v_mfma_f32_16x16x32_bf16 v[90:93], v[142:145], v[206:209], v[90:93]
	v_mfma_f32_16x16x32_bf16 v[82:85], v[134:137], v[214:217], v[82:85]
	v_mfma_f32_16x16x32_bf16 v[74:77], v[142:145], v[214:217], v[74:77]
	v_mfma_f32_16x16x32_bf16 v[118:121], v[146:149], v[176:179], v[118:121]
	v_mfma_f32_16x16x32_bf16 v[114:117], v[168:171], v[176:179], v[114:117]
	v_mfma_f32_16x16x32_bf16 v[102:105], v[146:149], v[184:187], v[102:105]
	v_mfma_f32_16x16x32_bf16 v[94:97], v[168:171], v[184:187], v[94:97]
	v_mfma_f32_16x16x32_bf16 v[86:89], v[146:149], v[202:205], v[86:89]
	v_mfma_f32_16x16x32_bf16 v[78:81], v[168:171], v[202:205], v[78:81]
	v_mfma_f32_16x16x32_bf16 v[70:73], v[146:149], v[210:213], v[70:73]
	v_mfma_f32_16x16x32_bf16 v[66:69], v[168:171], v[210:213], v[66:69]
	v_mfma_f32_16x16x32_bf16 v[118:121], v[164:167], v[180:183], v[118:121]
	v_mfma_f32_16x16x32_bf16 v[114:117], v[172:175], v[180:183], v[114:117]
	v_mfma_f32_16x16x32_bf16 v[102:105], v[164:167], v[190:193], v[102:105]
	v_mfma_f32_16x16x32_bf16 v[94:97], v[172:175], v[190:193], v[94:97]
	v_mfma_f32_16x16x32_bf16 v[86:89], v[164:167], v[206:209], v[86:89]
	v_mfma_f32_16x16x32_bf16 v[78:81], v[172:175], v[206:209], v[78:81]
	v_mfma_f32_16x16x32_bf16 v[70:73], v[164:167], v[214:217], v[70:73]
	v_mfma_f32_16x16x32_bf16 v[66:69], v[172:175], v[214:217], v[66:69]
	s_barrier
	s_setprio 0
	s_add_i32 s0, s46, s26
	s_mov_b32 m0, s0
	ds_read_b128 v[176:179], v189 offset:49152
	ds_read_b128 v[180:183], v189 offset:50176
	ds_read_b128 v[184:187], v189 offset:51200
	ds_read_b128 v[190:193], v189 offset:52224
	ds_read_b128 v[202:205], v189 offset:53248
	ds_read_b128 v[206:209], v189 offset:54272
	ds_read_b128 v[210:213], v189 offset:55296
	ds_read_b128 v[214:217], v189 offset:56320
	global_load_lds_dwordx4 v196, s[98:99]
	s_add_i32 m0, s0, 0x2000
	s_add_u32 s0, s48, 0x158080
	s_addc_u32 s1, s49, 0
	s_add_i32 s46, s47, s26
	global_load_lds_dwordx4 v154, s[98:99]
	s_mov_b32 m0, s46
	s_nop 0
	global_load_lds_dwordx4 v196, s[0:1]
	s_add_i32 m0, s46, 0x2000
	s_nop 0
	global_load_lds_dwordx4 v154, s[0:1]
	s_mov_b32 m0, s53
	s_nop 0
	global_load_lds_dwordx4 v150, s[78:79]
	s_mov_b32 m0, s58
	s_nop 0
	global_load_lds_dwordx4 v152, s[78:79]
	s_waitcnt vmcnt(8)
	s_waitcnt lgkmcnt(0)
	s_setprio 1
	s_barrier
	v_mfma_f32_16x16x32_bf16 v[62:65], v[130:133], v[176:179], v[62:65]
	v_mfma_f32_16x16x32_bf16 v[58:61], v[138:141], v[176:179], v[58:61]
	v_mfma_f32_16x16x32_bf16 v[50:53], v[130:133], v[184:187], v[50:53]
	v_mfma_f32_16x16x32_bf16 v[42:45], v[138:141], v[184:187], v[42:45]
	v_mfma_f32_16x16x32_bf16 v[34:37], v[130:133], v[202:205], v[34:37]
	v_mfma_f32_16x16x32_bf16 v[26:29], v[138:141], v[202:205], v[26:29]
	v_mfma_f32_16x16x32_bf16 v[18:21], v[130:133], v[210:213], v[18:21]
	v_mfma_f32_16x16x32_bf16 v[10:13], v[138:141], v[210:213], v[10:13]
	v_mfma_f32_16x16x32_bf16 v[62:65], v[134:137], v[180:183], v[62:65]
	v_mfma_f32_16x16x32_bf16 v[58:61], v[142:145], v[180:183], v[58:61]
	v_mfma_f32_16x16x32_bf16 v[50:53], v[134:137], v[190:193], v[50:53]
	v_mfma_f32_16x16x32_bf16 v[42:45], v[142:145], v[190:193], v[42:45]
	v_mfma_f32_16x16x32_bf16 v[34:37], v[134:137], v[206:209], v[34:37]
	v_mfma_f32_16x16x32_bf16 v[26:29], v[142:145], v[206:209], v[26:29]
	v_mfma_f32_16x16x32_bf16 v[18:21], v[134:137], v[214:217], v[18:21]
	v_mfma_f32_16x16x32_bf16 v[10:13], v[142:145], v[214:217], v[10:13]
	v_mfma_f32_16x16x32_bf16 v[54:57], v[146:149], v[176:179], v[54:57]
	v_mfma_f32_16x16x32_bf16 v[46:49], v[168:171], v[176:179], v[46:49]
	v_mfma_f32_16x16x32_bf16 v[38:41], v[146:149], v[184:187], v[38:41]
	v_mfma_f32_16x16x32_bf16 v[30:33], v[168:171], v[184:187], v[30:33]
	v_mfma_f32_16x16x32_bf16 v[22:25], v[146:149], v[202:205], v[22:25]
	v_mfma_f32_16x16x32_bf16 v[14:17], v[168:171], v[202:205], v[14:17]
	v_mfma_f32_16x16x32_bf16 v[6:9], v[146:149], v[210:213], v[6:9]
	v_mfma_f32_16x16x32_bf16 v[2:5], v[168:171], v[210:213], v[2:5]
	v_mfma_f32_16x16x32_bf16 v[54:57], v[164:167], v[180:183], v[54:57]
	v_mfma_f32_16x16x32_bf16 v[46:49], v[172:175], v[180:183], v[46:49]
	v_mfma_f32_16x16x32_bf16 v[38:41], v[164:167], v[190:193], v[38:41]
	v_mfma_f32_16x16x32_bf16 v[30:33], v[172:175], v[190:193], v[30:33]
	v_mfma_f32_16x16x32_bf16 v[22:25], v[164:167], v[206:209], v[22:25]
	v_mfma_f32_16x16x32_bf16 v[14:17], v[172:175], v[206:209], v[14:17]
	v_mfma_f32_16x16x32_bf16 v[6:9], v[164:167], v[214:217], v[6:9]
	v_mfma_f32_16x16x32_bf16 v[2:5], v[172:175], v[214:217], v[2:5]
	s_barrier
	s_setprio 0
	s_add_u32 s70, s70, 0x100
	s_addc_u32 s71, s71, 0
	s_cmp_ge_i32 s72, s69
	s_mov_b64 s[46:47], s[8:9]
	s_mov_b32 s48, s72
	s_cbranch_scc0 .LBB0_2588
	s_and_b64 vcc, exec, s[28:29]
	s_cbranch_vccz .LBB0_2591
	s_barrier
